# FFN-in swiglu epilogue: all 8 row-statistics loads issued up front, no per-row-block vmcnt(0) drain
# speedup vs baseline: 1.0035x; 1.0035x over previous
.LBB0_223:
	s_cmp_lt_i32 s22, 64
	s_cselect_b32 s15, s62, 0x2c00
	s_cmp_gt_i32 s22, 31
	s_cselect_b32 s15, s15, 0
	v_lshl_add_u32 v160, s22, 8, v168
	s_lshl_b32 s15, s15, 2
	s_add_u32 s15, s49, s15
	v_ashrrev_i32_e32 v161, 31, v160
	s_addc_u32 s17, s56, 0
	s_lshl_b32 s24, s64, 8
	v_lshl_add_u64 v[164:165], v[160:161], 2, s[6:7]
	s_ashr_i32 s25, s24, 31
	global_load_dword v161, v[164:165], off
	global_load_dword v241, v[164:165], off offset:64
	global_load_dword v242, v[164:165], off offset:128
	global_load_dword v243, v[164:165], off offset:192
	global_load_dword v244, v[164:165], off offset:512
	global_load_dword v245, v[164:165], off offset:576
	global_load_dword v246, v[164:165], off offset:640
	global_load_dword v247, v[164:165], off offset:704
	s_lshl_b64 s[24:25], s[24:25], 2
	s_add_u32 s15, s15, s24
	s_addc_u32 s17, s17, s25
	s_add_u32 s24, s15, s63
	s_addc_u32 s25, s17, 0
	global_load_dwordx4 v[112:115], v174, s[24:25]
	global_load_dwordx4 v[116:119], v174, s[24:25] offset:512
	global_load_dwordx4 v[104:107], v174, s[24:25] offset:16
	global_load_dwordx4 v[108:111], v174, s[24:25] offset:528
	v_or_b32_e32 v180, 16, v160
	v_ashrrev_i32_e32 v181, 31, v180
	v_lshl_add_u64 v[184:185], v[180:181], 2, s[6:7]
	v_lshl_or_b32 v166, s64, 7, v170
	v_mov_b64_e32 v[162:163], s[36:37]
	v_ashrrev_i32_e32 v167, 31, v166
	v_mad_i64_i32 v[178:179], s[24:25], v160, s62, v[162:163]
	v_lshlrev_b64 v[166:167], 1, v[166:167]
	v_lshl_add_u64 v[178:179], v[178:179], 0, v[166:167]
	s_andn2_b64 vcc, exec, s[2:3]
	s_mov_b64 s[2:3], -1
	s_waitcnt vmcnt(0)
	v_fmamk_f32 v161, v161, 0x3a800000, v175
	v_rsq_f32_e32 v182, v161
	s_nop 0
	v_pk_fma_f32 v[140:141], v[140:141], v[182:183], v[112:113] op_sel_hi:[1,0,1]
	v_pk_fma_f32 v[142:143], v[142:143], v[182:183], v[114:115] op_sel_hi:[1,0,1]
	v_pk_fma_f32 v[136:137], v[136:137], v[182:183], v[104:105] op_sel_hi:[1,0,1]
	v_pk_fma_f32 v[138:139], v[138:139], v[182:183], v[106:107] op_sel_hi:[1,0,1]
	v_pk_fma_f32 v[132:133], v[132:133], v[182:183], v[116:117] op_sel_hi:[1,0,1]
	v_pk_fma_f32 v[134:135], v[134:135], v[182:183], v[118:119] op_sel_hi:[1,0,1]
	v_pk_fma_f32 v[128:129], v[128:129], v[182:183], v[108:109] op_sel_hi:[1,0,1]
	v_pk_fma_f32 v[130:131], v[130:131], v[182:183], v[110:111] op_sel_hi:[1,0,1]
	v_mul_f32_e32 v161, 0xbfb8aa3b, v140
	v_mul_f32_e32 v177, 0xbfb8aa3b, v141
	v_mul_f32_e32 v181, 0xbfb8aa3b, v142
	v_mul_f32_e32 v182, 0xbfb8aa3b, v143
	v_mul_f32_e32 v183, 0xbfb8aa3b, v136
	v_mul_f32_e32 v186, 0xbfb8aa3b, v137
	v_mul_f32_e32 v187, 0xbfb8aa3b, v138
	v_mul_f32_e32 v188, 0xbfb8aa3b, v139
	v_exp_f32_e32 v161, v161
	v_exp_f32_e32 v177, v177
	v_exp_f32_e32 v181, v181
	v_exp_f32_e32 v182, v182
	v_exp_f32_e32 v183, v183
	v_exp_f32_e32 v186, v186
	v_exp_f32_e32 v187, v187
	v_exp_f32_e32 v188, v188
	v_add_f32_e32 v161, 1.0, v161
	v_add_f32_e32 v177, 1.0, v177
	v_add_f32_e32 v181, 1.0, v181
	v_add_f32_e32 v189, 1.0, v182
	v_add_f32_e32 v190, 1.0, v183
	v_add_f32_e32 v191, 1.0, v186
	v_add_f32_e32 v192, 1.0, v187
	v_add_f32_e32 v193, 1.0, v188
	v_rcp_f32_e32 v182, v161
	v_rcp_f32_e32 v183, v177
	v_rcp_f32_e32 v186, v181
	v_rcp_f32_e32 v187, v189
	v_rcp_f32_e32 v188, v190
	v_rcp_f32_e32 v189, v191
	v_rcp_f32_e32 v190, v192
	v_rcp_f32_e32 v191, v193
	v_pk_mul_f32 v[140:141], v[140:141], v[182:183]
	v_pk_mul_f32 v[142:143], v[142:143], v[186:187]
	v_pk_mul_f32 v[136:137], v[136:137], v[188:189]
	v_pk_mul_f32 v[138:139], v[138:139], v[190:191]
	v_pk_mul_f32 v[132:133], v[132:133], v[140:141]
	v_pk_mul_f32 v[134:135], v[134:135], v[142:143]
	v_pk_mul_f32 v[136:137], v[128:129], v[136:137]
	v_pk_mul_f32 v[138:139], v[130:131], v[138:139]
	v_cvt_pk_f16_f32 v128, v132, v133
	v_cvt_pk_f16_f32 v129, v134, v135
	v_cvt_pk_f16_f32 v130, v136, v137
	v_cvt_pk_f16_f32 v131, v138, v139
	global_store_dwordx4 v[178:179], v[128:131], off
	s_nop 0
	s_nop 0
	v_or_b32_e32 v128, 32, v160
	v_mad_i64_i32 v[130:131], s[24:25], v180, s62, v[162:163]
	v_lshl_add_u64 v[130:131], v[130:131], 0, v[166:167]
	v_fmamk_f32 v129, v241, 0x3a800000, v175
	v_rsq_f32_e32 v132, v129
	v_ashrrev_i32_e32 v129, 31, v128
	v_lshl_add_u64 v[134:135], v[128:129], 2, s[6:7]
	v_pk_fma_f32 v[124:125], v[124:125], v[132:133], v[112:113] op_sel_hi:[1,0,1]
	v_pk_fma_f32 v[126:127], v[126:127], v[132:133], v[114:115] op_sel_hi:[1,0,1]
	v_pk_fma_f32 v[120:121], v[120:121], v[132:133], v[104:105] op_sel_hi:[1,0,1]
	v_pk_fma_f32 v[122:123], v[122:123], v[132:133], v[106:107] op_sel_hi:[1,0,1]
	v_pk_fma_f32 v[100:101], v[100:101], v[132:133], v[116:117] op_sel_hi:[1,0,1]
	v_pk_fma_f32 v[102:103], v[102:103], v[132:133], v[118:119] op_sel_hi:[1,0,1]
	v_pk_fma_f32 v[96:97], v[96:97], v[132:133], v[108:109] op_sel_hi:[1,0,1]
	v_pk_fma_f32 v[98:99], v[98:99], v[132:133], v[110:111] op_sel_hi:[1,0,1]
	v_mul_f32_e32 v129, 0xbfb8aa3b, v124
	v_mul_f32_e32 v132, 0xbfb8aa3b, v125
	v_mul_f32_e32 v133, 0xbfb8aa3b, v126
	v_mul_f32_e32 v136, 0xbfb8aa3b, v127
	v_mul_f32_e32 v137, 0xbfb8aa3b, v120
	v_mul_f32_e32 v138, 0xbfb8aa3b, v121
	v_mul_f32_e32 v139, 0xbfb8aa3b, v122
	v_mul_f32_e32 v140, 0xbfb8aa3b, v123
	v_exp_f32_e32 v129, v129
	v_exp_f32_e32 v132, v132
	v_exp_f32_e32 v133, v133
	v_exp_f32_e32 v136, v136
	v_exp_f32_e32 v137, v137
	v_exp_f32_e32 v138, v138
	v_exp_f32_e32 v139, v139
	v_exp_f32_e32 v140, v140
	v_add_f32_e32 v129, 1.0, v129
	v_add_f32_e32 v141, 1.0, v132
	v_add_f32_e32 v142, 1.0, v133
	v_add_f32_e32 v143, 1.0, v136
	v_add_f32_e32 v161, 1.0, v137
	v_add_f32_e32 v177, 1.0, v138
	v_add_f32_e32 v178, 1.0, v139
	v_add_f32_e32 v179, 1.0, v140
	v_rcp_f32_e32 v132, v129
	v_rcp_f32_e32 v133, v141
	v_rcp_f32_e32 v136, v142
	v_rcp_f32_e32 v137, v143
	v_rcp_f32_e32 v138, v161
	v_rcp_f32_e32 v139, v177
	v_rcp_f32_e32 v140, v178
	v_rcp_f32_e32 v141, v179
	v_pk_mul_f32 v[124:125], v[124:125], v[132:133]
	v_pk_mul_f32 v[126:127], v[126:127], v[136:137]
	v_pk_mul_f32 v[120:121], v[120:121], v[138:139]
	v_pk_mul_f32 v[122:123], v[122:123], v[140:141]
	v_pk_mul_f32 v[100:101], v[100:101], v[124:125]
	v_pk_mul_f32 v[102:103], v[102:103], v[126:127]
	v_pk_mul_f32 v[120:121], v[96:97], v[120:121]
	v_pk_mul_f32 v[122:123], v[98:99], v[122:123]
	v_cvt_pk_f16_f32 v96, v100, v101
	v_cvt_pk_f16_f32 v97, v102, v103
	v_cvt_pk_f16_f32 v98, v120, v121
	v_cvt_pk_f16_f32 v99, v122, v123
	global_store_dwordx4 v[130:131], v[96:99], off
	s_nop 0
	s_nop 0
	v_or_b32_e32 v96, 48, v160
	v_mad_i64_i32 v[98:99], s[24:25], v128, s62, v[162:163]
	v_lshl_add_u64 v[98:99], v[98:99], 0, v[166:167]
	v_fmamk_f32 v97, v242, 0x3a800000, v175
	v_rsq_f32_e32 v100, v97
	v_ashrrev_i32_e32 v97, 31, v96
	v_lshl_add_u64 v[102:103], v[96:97], 2, s[6:7]
	v_pk_fma_f32 v[92:93], v[92:93], v[100:101], v[112:113] op_sel_hi:[1,0,1]
	v_pk_fma_f32 v[94:95], v[94:95], v[100:101], v[114:115] op_sel_hi:[1,0,1]
	v_pk_fma_f32 v[88:89], v[88:89], v[100:101], v[104:105] op_sel_hi:[1,0,1]
	v_pk_fma_f32 v[90:91], v[90:91], v[100:101], v[106:107] op_sel_hi:[1,0,1]
	v_pk_fma_f32 v[84:85], v[84:85], v[100:101], v[116:117] op_sel_hi:[1,0,1]
	v_pk_fma_f32 v[86:87], v[86:87], v[100:101], v[118:119] op_sel_hi:[1,0,1]
	v_pk_fma_f32 v[80:81], v[80:81], v[100:101], v[108:109] op_sel_hi:[1,0,1]
	v_pk_fma_f32 v[82:83], v[82:83], v[100:101], v[110:111] op_sel_hi:[1,0,1]
	v_mul_f32_e32 v97, 0xbfb8aa3b, v92
	v_mul_f32_e32 v100, 0xbfb8aa3b, v93
	v_mul_f32_e32 v101, 0xbfb8aa3b, v94
	v_mul_f32_e32 v120, 0xbfb8aa3b, v95
	v_mul_f32_e32 v121, 0xbfb8aa3b, v88
	v_mul_f32_e32 v122, 0xbfb8aa3b, v89
	v_mul_f32_e32 v123, 0xbfb8aa3b, v90
	v_mul_f32_e32 v124, 0xbfb8aa3b, v91
	v_exp_f32_e32 v97, v97
	v_exp_f32_e32 v100, v100
	v_exp_f32_e32 v101, v101
	v_exp_f32_e32 v120, v120
	v_exp_f32_e32 v121, v121
	v_exp_f32_e32 v122, v122
	v_exp_f32_e32 v123, v123
	v_exp_f32_e32 v124, v124
	v_add_f32_e32 v97, 1.0, v97
	v_add_f32_e32 v125, 1.0, v100
	v_add_f32_e32 v126, 1.0, v101
	v_add_f32_e32 v127, 1.0, v120
	v_add_f32_e32 v128, 1.0, v121
	v_add_f32_e32 v129, 1.0, v122
	v_add_f32_e32 v130, 1.0, v123
	v_add_f32_e32 v131, 1.0, v124
	v_rcp_f32_e32 v100, v97
	v_rcp_f32_e32 v101, v125
	v_rcp_f32_e32 v120, v126
	v_rcp_f32_e32 v121, v127
	v_rcp_f32_e32 v122, v128
	v_rcp_f32_e32 v123, v129
	v_rcp_f32_e32 v124, v130
	v_rcp_f32_e32 v125, v131
	v_pk_mul_f32 v[92:93], v[92:93], v[100:101]
	v_pk_mul_f32 v[94:95], v[94:95], v[120:121]
	v_pk_mul_f32 v[88:89], v[88:89], v[122:123]
	v_pk_mul_f32 v[90:91], v[90:91], v[124:125]
	v_pk_mul_f32 v[84:85], v[84:85], v[92:93]
	v_pk_mul_f32 v[86:87], v[86:87], v[94:95]
	v_pk_mul_f32 v[88:89], v[80:81], v[88:89]
	v_pk_mul_f32 v[90:91], v[82:83], v[90:91]
	v_cvt_pk_f16_f32 v80, v84, v85
	v_cvt_pk_f16_f32 v81, v86, v87
	v_cvt_pk_f16_f32 v82, v88, v89
	v_cvt_pk_f16_f32 v83, v90, v91
	global_store_dwordx4 v[98:99], v[80:83], off
	s_nop 0
	s_nop 0
	v_mad_i64_i32 v[82:83], s[24:25], v96, s62, v[162:163]
	v_lshl_add_u64 v[82:83], v[82:83], 0, v[166:167]
	v_fmamk_f32 v80, v243, 0x3a800000, v175
	v_rsq_f32_e32 v80, v80
	s_nop 0
	v_pk_fma_f32 v[76:77], v[76:77], v[80:81], v[112:113] op_sel_hi:[1,0,1]
	v_pk_fma_f32 v[78:79], v[78:79], v[80:81], v[114:115] op_sel_hi:[1,0,1]
	v_pk_fma_f32 v[72:73], v[72:73], v[80:81], v[104:105] op_sel_hi:[1,0,1]
	v_pk_fma_f32 v[74:75], v[74:75], v[80:81], v[106:107] op_sel_hi:[1,0,1]
	v_pk_fma_f32 v[68:69], v[68:69], v[80:81], v[116:117] op_sel_hi:[1,0,1]
	v_pk_fma_f32 v[70:71], v[70:71], v[80:81], v[118:119] op_sel_hi:[1,0,1]
	v_pk_fma_f32 v[64:65], v[64:65], v[80:81], v[108:109] op_sel_hi:[1,0,1]
	v_pk_fma_f32 v[66:67], v[66:67], v[80:81], v[110:111] op_sel_hi:[1,0,1]
	v_mul_f32_e32 v80, 0xbfb8aa3b, v76
	v_mul_f32_e32 v81, 0xbfb8aa3b, v77
	v_mul_f32_e32 v84, 0xbfb8aa3b, v78
	v_mul_f32_e32 v85, 0xbfb8aa3b, v79
	v_mul_f32_e32 v86, 0xbfb8aa3b, v72
	v_mul_f32_e32 v87, 0xbfb8aa3b, v73
	v_mul_f32_e32 v88, 0xbfb8aa3b, v74
	v_mul_f32_e32 v89, 0xbfb8aa3b, v75
	v_exp_f32_e32 v80, v80
	v_exp_f32_e32 v81, v81
	v_exp_f32_e32 v84, v84
	v_exp_f32_e32 v85, v85
	v_exp_f32_e32 v86, v86
	v_exp_f32_e32 v87, v87
	v_exp_f32_e32 v88, v88
	v_exp_f32_e32 v89, v89
	v_add_f32_e32 v80, 1.0, v80
	v_add_f32_e32 v81, 1.0, v81
	v_add_f32_e32 v84, 1.0, v84
	v_add_f32_e32 v85, 1.0, v85
	v_add_f32_e32 v86, 1.0, v86
	v_add_f32_e32 v87, 1.0, v87
	v_add_f32_e32 v88, 1.0, v88
	v_add_f32_e32 v89, 1.0, v89
	v_rcp_f32_e32 v80, v80
	v_rcp_f32_e32 v81, v81
	v_rcp_f32_e32 v84, v84
	v_rcp_f32_e32 v85, v85
	v_rcp_f32_e32 v86, v86
	v_rcp_f32_e32 v87, v87
	v_rcp_f32_e32 v88, v88
	v_rcp_f32_e32 v89, v89
	v_pk_mul_f32 v[76:77], v[76:77], v[80:81]
	v_pk_mul_f32 v[78:79], v[78:79], v[84:85]
	v_pk_mul_f32 v[72:73], v[72:73], v[86:87]
	v_pk_mul_f32 v[74:75], v[74:75], v[88:89]
	v_pk_mul_f32 v[68:69], v[68:69], v[76:77]
	v_pk_mul_f32 v[70:71], v[70:71], v[78:79]
	v_pk_mul_f32 v[72:73], v[64:65], v[72:73]
	v_pk_mul_f32 v[74:75], v[66:67], v[74:75]
	v_cvt_pk_f16_f32 v64, v68, v69
	v_cvt_pk_f16_f32 v65, v70, v71
	v_cvt_pk_f16_f32 v66, v72, v73
	v_cvt_pk_f16_f32 v67, v74, v75
	global_store_dwordx4 v[82:83], v[64:67], off
	s_nop 0
	s_nop 0
	v_add_u32_e32 v65, 0x80, v160
	v_mad_i64_i32 v[66:67], s[24:25], v65, s62, v[162:163]
	v_lshl_add_u64 v[66:67], v[66:67], 0, v[166:167]
	v_fmamk_f32 v64, v244, 0x3a800000, v175
	v_rsq_f32_e32 v64, v64
	s_nop 0
	v_pk_fma_f32 v[60:61], v[60:61], v[64:65], v[112:113] op_sel_hi:[1,0,1]
	v_pk_fma_f32 v[62:63], v[62:63], v[64:65], v[114:115] op_sel_hi:[1,0,1]
	v_pk_fma_f32 v[56:57], v[56:57], v[64:65], v[104:105] op_sel_hi:[1,0,1]
	v_pk_fma_f32 v[58:59], v[58:59], v[64:65], v[106:107] op_sel_hi:[1,0,1]
	v_pk_fma_f32 v[52:53], v[52:53], v[64:65], v[116:117] op_sel_hi:[1,0,1]
	v_pk_fma_f32 v[54:55], v[54:55], v[64:65], v[118:119] op_sel_hi:[1,0,1]
	v_pk_fma_f32 v[48:49], v[48:49], v[64:65], v[108:109] op_sel_hi:[1,0,1]
	v_pk_fma_f32 v[50:51], v[50:51], v[64:65], v[110:111] op_sel_hi:[1,0,1]
	v_mul_f32_e32 v64, 0xbfb8aa3b, v60
	v_mul_f32_e32 v65, 0xbfb8aa3b, v61
	v_mul_f32_e32 v68, 0xbfb8aa3b, v62
	v_mul_f32_e32 v69, 0xbfb8aa3b, v63
	v_mul_f32_e32 v70, 0xbfb8aa3b, v56
	v_mul_f32_e32 v71, 0xbfb8aa3b, v57
	v_mul_f32_e32 v72, 0xbfb8aa3b, v58
	v_mul_f32_e32 v73, 0xbfb8aa3b, v59
	v_exp_f32_e32 v64, v64
	v_exp_f32_e32 v65, v65
	v_exp_f32_e32 v68, v68
	v_exp_f32_e32 v69, v69
	v_exp_f32_e32 v70, v70
	v_exp_f32_e32 v71, v71
	v_exp_f32_e32 v72, v72
	v_exp_f32_e32 v73, v73
	v_add_f32_e32 v64, 1.0, v64
	v_add_f32_e32 v65, 1.0, v65
	v_add_f32_e32 v68, 1.0, v68
	v_add_f32_e32 v69, 1.0, v69
	v_add_f32_e32 v70, 1.0, v70
	v_add_f32_e32 v71, 1.0, v71
	v_add_f32_e32 v72, 1.0, v72
	v_add_f32_e32 v73, 1.0, v73
	v_rcp_f32_e32 v64, v64
	v_rcp_f32_e32 v65, v65
	v_rcp_f32_e32 v68, v68
	v_rcp_f32_e32 v69, v69
	v_rcp_f32_e32 v70, v70
	v_rcp_f32_e32 v71, v71
	v_rcp_f32_e32 v72, v72
	v_rcp_f32_e32 v73, v73
	v_pk_mul_f32 v[60:61], v[60:61], v[64:65]
	v_pk_mul_f32 v[62:63], v[62:63], v[68:69]
	v_pk_mul_f32 v[56:57], v[56:57], v[70:71]
	v_pk_mul_f32 v[58:59], v[58:59], v[72:73]
	v_pk_mul_f32 v[52:53], v[52:53], v[60:61]
	v_pk_mul_f32 v[54:55], v[54:55], v[62:63]
	v_pk_mul_f32 v[56:57], v[48:49], v[56:57]
	v_pk_mul_f32 v[58:59], v[50:51], v[58:59]
	v_cvt_pk_f16_f32 v48, v52, v53
	v_cvt_pk_f16_f32 v49, v54, v55
	v_cvt_pk_f16_f32 v50, v56, v57
	v_cvt_pk_f16_f32 v51, v58, v59
	global_store_dwordx4 v[66:67], v[48:51], off
	s_nop 0
	s_nop 0
	v_add_u32_e32 v49, 0x90, v160
	v_mad_i64_i32 v[50:51], s[24:25], v49, s62, v[162:163]
	v_lshl_add_u64 v[50:51], v[50:51], 0, v[166:167]
	v_fmamk_f32 v48, v245, 0x3a800000, v175
	v_rsq_f32_e32 v48, v48
	s_nop 0
	v_pk_fma_f32 v[44:45], v[44:45], v[48:49], v[112:113] op_sel_hi:[1,0,1]
	v_pk_fma_f32 v[46:47], v[46:47], v[48:49], v[114:115] op_sel_hi:[1,0,1]
	v_pk_fma_f32 v[40:41], v[40:41], v[48:49], v[104:105] op_sel_hi:[1,0,1]
	v_pk_fma_f32 v[42:43], v[42:43], v[48:49], v[106:107] op_sel_hi:[1,0,1]
	v_pk_fma_f32 v[36:37], v[36:37], v[48:49], v[116:117] op_sel_hi:[1,0,1]
	v_pk_fma_f32 v[38:39], v[38:39], v[48:49], v[118:119] op_sel_hi:[1,0,1]
	v_pk_fma_f32 v[32:33], v[32:33], v[48:49], v[108:109] op_sel_hi:[1,0,1]
	v_pk_fma_f32 v[34:35], v[34:35], v[48:49], v[110:111] op_sel_hi:[1,0,1]
	v_mul_f32_e32 v48, 0xbfb8aa3b, v44
	v_mul_f32_e32 v49, 0xbfb8aa3b, v45
	v_mul_f32_e32 v52, 0xbfb8aa3b, v46
	v_mul_f32_e32 v53, 0xbfb8aa3b, v47
	v_mul_f32_e32 v54, 0xbfb8aa3b, v40
	v_mul_f32_e32 v55, 0xbfb8aa3b, v41
	v_mul_f32_e32 v56, 0xbfb8aa3b, v42
	v_mul_f32_e32 v57, 0xbfb8aa3b, v43
	v_exp_f32_e32 v48, v48
	v_exp_f32_e32 v49, v49
	v_exp_f32_e32 v52, v52
	v_exp_f32_e32 v53, v53
	v_exp_f32_e32 v54, v54
	v_exp_f32_e32 v55, v55
	v_exp_f32_e32 v56, v56
	v_exp_f32_e32 v57, v57
	v_add_f32_e32 v48, 1.0, v48
	v_add_f32_e32 v49, 1.0, v49
	v_add_f32_e32 v52, 1.0, v52
	v_add_f32_e32 v53, 1.0, v53
	v_add_f32_e32 v54, 1.0, v54
	v_add_f32_e32 v55, 1.0, v55
	v_add_f32_e32 v56, 1.0, v56
	v_add_f32_e32 v57, 1.0, v57
	v_rcp_f32_e32 v48, v48
	v_rcp_f32_e32 v49, v49
	v_rcp_f32_e32 v52, v52
	v_rcp_f32_e32 v53, v53
	v_rcp_f32_e32 v54, v54
	v_rcp_f32_e32 v55, v55
	v_rcp_f32_e32 v56, v56
	v_rcp_f32_e32 v57, v57
	v_pk_mul_f32 v[44:45], v[44:45], v[48:49]
	v_pk_mul_f32 v[46:47], v[46:47], v[52:53]
	v_pk_mul_f32 v[40:41], v[40:41], v[54:55]
	v_pk_mul_f32 v[42:43], v[42:43], v[56:57]
	v_pk_mul_f32 v[36:37], v[36:37], v[44:45]
	v_pk_mul_f32 v[38:39], v[38:39], v[46:47]
	v_pk_mul_f32 v[40:41], v[32:33], v[40:41]
	v_pk_mul_f32 v[42:43], v[34:35], v[42:43]
	v_cvt_pk_f16_f32 v32, v36, v37
	v_cvt_pk_f16_f32 v33, v38, v39
	v_cvt_pk_f16_f32 v34, v40, v41
	v_cvt_pk_f16_f32 v35, v42, v43
	global_store_dwordx4 v[50:51], v[32:35], off
	s_nop 0
	s_nop 0
	v_add_u32_e32 v33, 0xa0, v160
	v_mad_i64_i32 v[34:35], s[24:25], v33, s62, v[162:163]
	v_lshl_add_u64 v[34:35], v[34:35], 0, v[166:167]
	v_fmamk_f32 v32, v246, 0x3a800000, v175
	v_rsq_f32_e32 v32, v32
	s_nop 0
	v_pk_fma_f32 v[28:29], v[28:29], v[32:33], v[112:113] op_sel_hi:[1,0,1]
	v_pk_fma_f32 v[30:31], v[30:31], v[32:33], v[114:115] op_sel_hi:[1,0,1]
	v_pk_fma_f32 v[24:25], v[24:25], v[32:33], v[104:105] op_sel_hi:[1,0,1]
	v_pk_fma_f32 v[26:27], v[26:27], v[32:33], v[106:107] op_sel_hi:[1,0,1]
	v_pk_fma_f32 v[20:21], v[20:21], v[32:33], v[116:117] op_sel_hi:[1,0,1]
	v_pk_fma_f32 v[22:23], v[22:23], v[32:33], v[118:119] op_sel_hi:[1,0,1]
	v_pk_fma_f32 v[16:17], v[16:17], v[32:33], v[108:109] op_sel_hi:[1,0,1]
	v_pk_fma_f32 v[18:19], v[18:19], v[32:33], v[110:111] op_sel_hi:[1,0,1]
	v_mul_f32_e32 v32, 0xbfb8aa3b, v28
	v_mul_f32_e32 v33, 0xbfb8aa3b, v29
	v_mul_f32_e32 v36, 0xbfb8aa3b, v30
	v_mul_f32_e32 v37, 0xbfb8aa3b, v31
	v_mul_f32_e32 v38, 0xbfb8aa3b, v24
	v_mul_f32_e32 v39, 0xbfb8aa3b, v25
	v_mul_f32_e32 v40, 0xbfb8aa3b, v26
	v_mul_f32_e32 v41, 0xbfb8aa3b, v27
	v_exp_f32_e32 v32, v32
	v_exp_f32_e32 v33, v33
	v_exp_f32_e32 v36, v36
	v_exp_f32_e32 v37, v37
	v_exp_f32_e32 v38, v38
	v_exp_f32_e32 v39, v39
	v_exp_f32_e32 v40, v40
	v_exp_f32_e32 v41, v41
	v_add_f32_e32 v32, 1.0, v32
	v_add_f32_e32 v33, 1.0, v33
	v_add_f32_e32 v36, 1.0, v36
	v_add_f32_e32 v37, 1.0, v37
	v_add_f32_e32 v38, 1.0, v38
	v_add_f32_e32 v39, 1.0, v39
	v_add_f32_e32 v40, 1.0, v40
	v_add_f32_e32 v41, 1.0, v41
	v_rcp_f32_e32 v32, v32
	v_rcp_f32_e32 v33, v33
	v_rcp_f32_e32 v36, v36
	v_rcp_f32_e32 v37, v37
	v_rcp_f32_e32 v38, v38
	v_rcp_f32_e32 v39, v39
	v_rcp_f32_e32 v40, v40
	v_rcp_f32_e32 v41, v41
	v_pk_mul_f32 v[28:29], v[28:29], v[32:33]
	v_pk_mul_f32 v[30:31], v[30:31], v[36:37]
	v_pk_mul_f32 v[24:25], v[24:25], v[38:39]
	v_pk_mul_f32 v[26:27], v[26:27], v[40:41]
	v_pk_mul_f32 v[20:21], v[20:21], v[28:29]
	v_pk_mul_f32 v[22:23], v[22:23], v[30:31]
	v_pk_mul_f32 v[24:25], v[16:17], v[24:25]
	v_pk_mul_f32 v[26:27], v[18:19], v[26:27]
	v_cvt_pk_f16_f32 v16, v20, v21
	v_cvt_pk_f16_f32 v17, v22, v23
	v_cvt_pk_f16_f32 v18, v24, v25
	v_cvt_pk_f16_f32 v19, v26, v27
	global_store_dwordx4 v[34:35], v[16:19], off
	s_nop 0
	s_nop 0
	v_add_u32_e32 v17, 0xb0, v160
	v_mad_i64_i32 v[18:19], s[24:25], v17, s62, v[162:163]
	v_lshl_add_u64 v[18:19], v[18:19], 0, v[166:167]
	v_fmamk_f32 v16, v247, 0x3a800000, v175
	v_rsq_f32_e32 v16, v16
	s_nop 0
	v_pk_fma_f32 v[12:13], v[12:13], v[16:17], v[112:113] op_sel_hi:[1,0,1]
	v_pk_fma_f32 v[14:15], v[14:15], v[16:17], v[114:115] op_sel_hi:[1,0,1]
	v_pk_fma_f32 v[8:9], v[8:9], v[16:17], v[104:105] op_sel_hi:[1,0,1]
	v_pk_fma_f32 v[10:11], v[10:11], v[16:17], v[106:107] op_sel_hi:[1,0,1]
	v_pk_fma_f32 v[4:5], v[4:5], v[16:17], v[116:117] op_sel_hi:[1,0,1]
	v_pk_fma_f32 v[6:7], v[6:7], v[16:17], v[118:119] op_sel_hi:[1,0,1]
	v_pk_fma_f32 v[0:1], v[0:1], v[16:17], v[108:109] op_sel_hi:[1,0,1]
	v_pk_fma_f32 v[2:3], v[2:3], v[16:17], v[110:111] op_sel_hi:[1,0,1]
	v_mul_f32_e32 v16, 0xbfb8aa3b, v12
	v_mul_f32_e32 v17, 0xbfb8aa3b, v13
	v_mul_f32_e32 v20, 0xbfb8aa3b, v14
	v_mul_f32_e32 v21, 0xbfb8aa3b, v15
	v_mul_f32_e32 v22, 0xbfb8aa3b, v8
	v_mul_f32_e32 v23, 0xbfb8aa3b, v9
	v_mul_f32_e32 v24, 0xbfb8aa3b, v10
	v_mul_f32_e32 v25, 0xbfb8aa3b, v11
	v_exp_f32_e32 v16, v16
	v_exp_f32_e32 v17, v17
	v_exp_f32_e32 v20, v20
	v_exp_f32_e32 v21, v21
	v_exp_f32_e32 v22, v22
	v_exp_f32_e32 v23, v23
	v_exp_f32_e32 v24, v24
	v_exp_f32_e32 v25, v25
	v_add_f32_e32 v16, 1.0, v16
	v_add_f32_e32 v17, 1.0, v17
	v_add_f32_e32 v20, 1.0, v20
	v_add_f32_e32 v21, 1.0, v21
	v_add_f32_e32 v22, 1.0, v22
	v_add_f32_e32 v23, 1.0, v23
	v_add_f32_e32 v24, 1.0, v24
	v_add_f32_e32 v25, 1.0, v25
	v_rcp_f32_e32 v16, v16
	v_rcp_f32_e32 v17, v17
	v_rcp_f32_e32 v20, v20
	v_rcp_f32_e32 v21, v21
	v_rcp_f32_e32 v22, v22
	v_rcp_f32_e32 v23, v23
	v_rcp_f32_e32 v24, v24
	v_rcp_f32_e32 v25, v25
	v_pk_mul_f32 v[12:13], v[12:13], v[16:17]
	v_pk_mul_f32 v[14:15], v[14:15], v[20:21]
	v_pk_mul_f32 v[8:9], v[8:9], v[22:23]
	v_pk_mul_f32 v[10:11], v[10:11], v[24:25]
	v_pk_mul_f32 v[4:5], v[4:5], v[12:13]
	v_pk_mul_f32 v[6:7], v[6:7], v[14:15]
	v_pk_mul_f32 v[8:9], v[0:1], v[8:9]
	v_pk_mul_f32 v[10:11], v[2:3], v[10:11]
	v_cvt_pk_f16_f32 v0, v4, v5
	v_cvt_pk_f16_f32 v1, v6, v7
	v_cvt_pk_f16_f32 v2, v8, v9
	v_cvt_pk_f16_f32 v3, v10, v11
	global_store_dwordx4 v[18:19], v[0:3], off
	s_cbranch_vccnz .LBB0_212
	s_andn2_b64 vcc, exec, s[4:5]
	s_cbranch_vccnz .LBB0_211
	s_barrier
	s_branch .LBB0_211

.LBB0_876:
	s_cmp_lt_i32 s22, 64
	s_cselect_b32 s15, s60, 0x2c00
	s_cmp_gt_i32 s22, 31
	s_cselect_b32 s15, s15, 0
	v_lshl_add_u32 v160, s22, 8, v168
	s_lshl_b32 s15, s15, 2
	s_add_u32 s15, s49, s15
	v_ashrrev_i32_e32 v161, 31, v160
	s_addc_u32 s17, s54, 0
	s_lshl_b32 s24, s62, 8
	v_lshl_add_u64 v[164:165], v[160:161], 2, s[6:7]
	s_ashr_i32 s25, s24, 31
	global_load_dword v161, v[164:165], off
	global_load_dword v241, v[164:165], off offset:64
	global_load_dword v242, v[164:165], off offset:128
	global_load_dword v243, v[164:165], off offset:192
	global_load_dword v244, v[164:165], off offset:512
	global_load_dword v245, v[164:165], off offset:576
	global_load_dword v246, v[164:165], off offset:640
	global_load_dword v247, v[164:165], off offset:704
	s_lshl_b64 s[24:25], s[24:25], 2
	s_add_u32 s15, s15, s24
	s_addc_u32 s17, s17, s25
	s_add_u32 s24, s15, s61
	s_addc_u32 s25, s17, 0
	global_load_dwordx4 v[112:115], v174, s[24:25]
	global_load_dwordx4 v[116:119], v174, s[24:25] offset:512
	global_load_dwordx4 v[104:107], v174, s[24:25] offset:16
	global_load_dwordx4 v[108:111], v174, s[24:25] offset:528
	v_or_b32_e32 v180, 16, v160
	v_ashrrev_i32_e32 v181, 31, v180
	v_lshl_add_u64 v[184:185], v[180:181], 2, s[6:7]
	v_lshl_or_b32 v166, s62, 7, v170
	v_mov_b64_e32 v[162:163], s[36:37]
	v_ashrrev_i32_e32 v167, 31, v166
	v_mad_i64_i32 v[178:179], s[24:25], v160, s60, v[162:163]
	v_lshlrev_b64 v[166:167], 1, v[166:167]
	v_lshl_add_u64 v[178:179], v[178:179], 0, v[166:167]
	s_andn2_b64 vcc, exec, s[2:3]
	s_mov_b64 s[2:3], -1
	s_waitcnt vmcnt(0)
	v_fmamk_f32 v161, v161, 0x3a800000, v175
	v_rsq_f32_e32 v182, v161
	s_nop 0
	v_pk_fma_f32 v[140:141], v[140:141], v[182:183], v[112:113] op_sel_hi:[1,0,1]
	v_pk_fma_f32 v[142:143], v[142:143], v[182:183], v[114:115] op_sel_hi:[1,0,1]
	v_pk_fma_f32 v[136:137], v[136:137], v[182:183], v[104:105] op_sel_hi:[1,0,1]
	v_pk_fma_f32 v[138:139], v[138:139], v[182:183], v[106:107] op_sel_hi:[1,0,1]
	v_pk_fma_f32 v[132:133], v[132:133], v[182:183], v[116:117] op_sel_hi:[1,0,1]
	v_pk_fma_f32 v[134:135], v[134:135], v[182:183], v[118:119] op_sel_hi:[1,0,1]
	v_pk_fma_f32 v[128:129], v[128:129], v[182:183], v[108:109] op_sel_hi:[1,0,1]
	v_pk_fma_f32 v[130:131], v[130:131], v[182:183], v[110:111] op_sel_hi:[1,0,1]
	v_mul_f32_e32 v161, 0xbfb8aa3b, v140
	v_mul_f32_e32 v177, 0xbfb8aa3b, v141
	v_mul_f32_e32 v181, 0xbfb8aa3b, v142
	v_mul_f32_e32 v182, 0xbfb8aa3b, v143
	v_mul_f32_e32 v183, 0xbfb8aa3b, v136
	v_mul_f32_e32 v186, 0xbfb8aa3b, v137
	v_mul_f32_e32 v187, 0xbfb8aa3b, v138
	v_mul_f32_e32 v188, 0xbfb8aa3b, v139
	v_exp_f32_e32 v161, v161
	v_exp_f32_e32 v177, v177
	v_exp_f32_e32 v181, v181
	v_exp_f32_e32 v182, v182
	v_exp_f32_e32 v183, v183
	v_exp_f32_e32 v186, v186
	v_exp_f32_e32 v187, v187
	v_exp_f32_e32 v188, v188
	v_add_f32_e32 v161, 1.0, v161
	v_add_f32_e32 v177, 1.0, v177
	v_add_f32_e32 v181, 1.0, v181
	v_add_f32_e32 v189, 1.0, v182
	v_add_f32_e32 v190, 1.0, v183
	v_add_f32_e32 v191, 1.0, v186
	v_add_f32_e32 v192, 1.0, v187
	v_add_f32_e32 v193, 1.0, v188
	v_rcp_f32_e32 v182, v161
	v_rcp_f32_e32 v183, v177
	v_rcp_f32_e32 v186, v181
	v_rcp_f32_e32 v187, v189
	v_rcp_f32_e32 v188, v190
	v_rcp_f32_e32 v189, v191
	v_rcp_f32_e32 v190, v192
	v_rcp_f32_e32 v191, v193
	v_pk_mul_f32 v[140:141], v[140:141], v[182:183]
	v_pk_mul_f32 v[142:143], v[142:143], v[186:187]
	v_pk_mul_f32 v[136:137], v[136:137], v[188:189]
	v_pk_mul_f32 v[138:139], v[138:139], v[190:191]
	v_pk_mul_f32 v[132:133], v[132:133], v[140:141]
	v_pk_mul_f32 v[134:135], v[134:135], v[142:143]
	v_pk_mul_f32 v[136:137], v[128:129], v[136:137]
	v_pk_mul_f32 v[138:139], v[130:131], v[138:139]
	v_cvt_pk_f16_f32 v128, v132, v133
	v_cvt_pk_f16_f32 v129, v134, v135
	v_cvt_pk_f16_f32 v130, v136, v137
	v_cvt_pk_f16_f32 v131, v138, v139
	global_store_dwordx4 v[178:179], v[128:131], off
	s_nop 0
	s_nop 0
	v_or_b32_e32 v128, 32, v160
	v_mad_i64_i32 v[130:131], s[24:25], v180, s60, v[162:163]
	v_lshl_add_u64 v[130:131], v[130:131], 0, v[166:167]
	v_fmamk_f32 v129, v241, 0x3a800000, v175
	v_rsq_f32_e32 v132, v129
	v_ashrrev_i32_e32 v129, 31, v128
	v_lshl_add_u64 v[134:135], v[128:129], 2, s[6:7]
	v_pk_fma_f32 v[124:125], v[124:125], v[132:133], v[112:113] op_sel_hi:[1,0,1]
	v_pk_fma_f32 v[126:127], v[126:127], v[132:133], v[114:115] op_sel_hi:[1,0,1]
	v_pk_fma_f32 v[120:121], v[120:121], v[132:133], v[104:105] op_sel_hi:[1,0,1]
	v_pk_fma_f32 v[122:123], v[122:123], v[132:133], v[106:107] op_sel_hi:[1,0,1]
	v_pk_fma_f32 v[100:101], v[100:101], v[132:133], v[116:117] op_sel_hi:[1,0,1]
	v_pk_fma_f32 v[102:103], v[102:103], v[132:133], v[118:119] op_sel_hi:[1,0,1]
	v_pk_fma_f32 v[96:97], v[96:97], v[132:133], v[108:109] op_sel_hi:[1,0,1]
	v_pk_fma_f32 v[98:99], v[98:99], v[132:133], v[110:111] op_sel_hi:[1,0,1]
	v_mul_f32_e32 v129, 0xbfb8aa3b, v124
	v_mul_f32_e32 v132, 0xbfb8aa3b, v125
	v_mul_f32_e32 v133, 0xbfb8aa3b, v126
	v_mul_f32_e32 v136, 0xbfb8aa3b, v127
	v_mul_f32_e32 v137, 0xbfb8aa3b, v120
	v_mul_f32_e32 v138, 0xbfb8aa3b, v121
	v_mul_f32_e32 v139, 0xbfb8aa3b, v122
	v_mul_f32_e32 v140, 0xbfb8aa3b, v123
	v_exp_f32_e32 v129, v129
	v_exp_f32_e32 v132, v132
	v_exp_f32_e32 v133, v133
	v_exp_f32_e32 v136, v136
	v_exp_f32_e32 v137, v137
	v_exp_f32_e32 v138, v138
	v_exp_f32_e32 v139, v139
	v_exp_f32_e32 v140, v140
	v_add_f32_e32 v129, 1.0, v129
	v_add_f32_e32 v141, 1.0, v132
	v_add_f32_e32 v142, 1.0, v133
	v_add_f32_e32 v143, 1.0, v136
	v_add_f32_e32 v161, 1.0, v137
	v_add_f32_e32 v177, 1.0, v138
	v_add_f32_e32 v178, 1.0, v139
	v_add_f32_e32 v179, 1.0, v140
	v_rcp_f32_e32 v132, v129
	v_rcp_f32_e32 v133, v141
	v_rcp_f32_e32 v136, v142
	v_rcp_f32_e32 v137, v143
	v_rcp_f32_e32 v138, v161
	v_rcp_f32_e32 v139, v177
	v_rcp_f32_e32 v140, v178
	v_rcp_f32_e32 v141, v179
	v_pk_mul_f32 v[124:125], v[124:125], v[132:133]
	v_pk_mul_f32 v[126:127], v[126:127], v[136:137]
	v_pk_mul_f32 v[120:121], v[120:121], v[138:139]
	v_pk_mul_f32 v[122:123], v[122:123], v[140:141]
	v_pk_mul_f32 v[100:101], v[100:101], v[124:125]
	v_pk_mul_f32 v[102:103], v[102:103], v[126:127]
	v_pk_mul_f32 v[120:121], v[96:97], v[120:121]
	v_pk_mul_f32 v[122:123], v[98:99], v[122:123]
	v_cvt_pk_f16_f32 v96, v100, v101
	v_cvt_pk_f16_f32 v97, v102, v103
	v_cvt_pk_f16_f32 v98, v120, v121
	v_cvt_pk_f16_f32 v99, v122, v123
	global_store_dwordx4 v[130:131], v[96:99], off
	s_nop 0
	s_nop 0
	v_or_b32_e32 v96, 48, v160
	v_mad_i64_i32 v[98:99], s[24:25], v128, s60, v[162:163]
	v_lshl_add_u64 v[98:99], v[98:99], 0, v[166:167]
	v_fmamk_f32 v97, v242, 0x3a800000, v175
	v_rsq_f32_e32 v100, v97
	v_ashrrev_i32_e32 v97, 31, v96
	v_lshl_add_u64 v[102:103], v[96:97], 2, s[6:7]
	v_pk_fma_f32 v[92:93], v[92:93], v[100:101], v[112:113] op_sel_hi:[1,0,1]
	v_pk_fma_f32 v[94:95], v[94:95], v[100:101], v[114:115] op_sel_hi:[1,0,1]
	v_pk_fma_f32 v[88:89], v[88:89], v[100:101], v[104:105] op_sel_hi:[1,0,1]
	v_pk_fma_f32 v[90:91], v[90:91], v[100:101], v[106:107] op_sel_hi:[1,0,1]
	v_pk_fma_f32 v[84:85], v[84:85], v[100:101], v[116:117] op_sel_hi:[1,0,1]
	v_pk_fma_f32 v[86:87], v[86:87], v[100:101], v[118:119] op_sel_hi:[1,0,1]
	v_pk_fma_f32 v[80:81], v[80:81], v[100:101], v[108:109] op_sel_hi:[1,0,1]
	v_pk_fma_f32 v[82:83], v[82:83], v[100:101], v[110:111] op_sel_hi:[1,0,1]
	v_mul_f32_e32 v97, 0xbfb8aa3b, v92
	v_mul_f32_e32 v100, 0xbfb8aa3b, v93
	v_mul_f32_e32 v101, 0xbfb8aa3b, v94
	v_mul_f32_e32 v120, 0xbfb8aa3b, v95
	v_mul_f32_e32 v121, 0xbfb8aa3b, v88
	v_mul_f32_e32 v122, 0xbfb8aa3b, v89
	v_mul_f32_e32 v123, 0xbfb8aa3b, v90
	v_mul_f32_e32 v124, 0xbfb8aa3b, v91
	v_exp_f32_e32 v97, v97
	v_exp_f32_e32 v100, v100
	v_exp_f32_e32 v101, v101
	v_exp_f32_e32 v120, v120
	v_exp_f32_e32 v121, v121
	v_exp_f32_e32 v122, v122
	v_exp_f32_e32 v123, v123
	v_exp_f32_e32 v124, v124
	v_add_f32_e32 v97, 1.0, v97
	v_add_f32_e32 v125, 1.0, v100
	v_add_f32_e32 v126, 1.0, v101
	v_add_f32_e32 v127, 1.0, v120
	v_add_f32_e32 v128, 1.0, v121
	v_add_f32_e32 v129, 1.0, v122
	v_add_f32_e32 v130, 1.0, v123
	v_add_f32_e32 v131, 1.0, v124
	v_rcp_f32_e32 v100, v97
	v_rcp_f32_e32 v101, v125
	v_rcp_f32_e32 v120, v126
	v_rcp_f32_e32 v121, v127
	v_rcp_f32_e32 v122, v128
	v_rcp_f32_e32 v123, v129
	v_rcp_f32_e32 v124, v130
	v_rcp_f32_e32 v125, v131
	v_pk_mul_f32 v[92:93], v[92:93], v[100:101]
	v_pk_mul_f32 v[94:95], v[94:95], v[120:121]
	v_pk_mul_f32 v[88:89], v[88:89], v[122:123]
	v_pk_mul_f32 v[90:91], v[90:91], v[124:125]
	v_pk_mul_f32 v[84:85], v[84:85], v[92:93]
	v_pk_mul_f32 v[86:87], v[86:87], v[94:95]
	v_pk_mul_f32 v[88:89], v[80:81], v[88:89]
	v_pk_mul_f32 v[90:91], v[82:83], v[90:91]
	v_cvt_pk_f16_f32 v80, v84, v85
	v_cvt_pk_f16_f32 v81, v86, v87
	v_cvt_pk_f16_f32 v82, v88, v89
	v_cvt_pk_f16_f32 v83, v90, v91
	global_store_dwordx4 v[98:99], v[80:83], off
	s_nop 0
	s_nop 0
	v_mad_i64_i32 v[82:83], s[24:25], v96, s60, v[162:163]
	v_lshl_add_u64 v[82:83], v[82:83], 0, v[166:167]
	v_fmamk_f32 v80, v243, 0x3a800000, v175
	v_rsq_f32_e32 v80, v80
	s_nop 0
	v_pk_fma_f32 v[76:77], v[76:77], v[80:81], v[112:113] op_sel_hi:[1,0,1]
	v_pk_fma_f32 v[78:79], v[78:79], v[80:81], v[114:115] op_sel_hi:[1,0,1]
	v_pk_fma_f32 v[72:73], v[72:73], v[80:81], v[104:105] op_sel_hi:[1,0,1]
	v_pk_fma_f32 v[74:75], v[74:75], v[80:81], v[106:107] op_sel_hi:[1,0,1]
	v_pk_fma_f32 v[68:69], v[68:69], v[80:81], v[116:117] op_sel_hi:[1,0,1]
	v_pk_fma_f32 v[70:71], v[70:71], v[80:81], v[118:119] op_sel_hi:[1,0,1]
	v_pk_fma_f32 v[64:65], v[64:65], v[80:81], v[108:109] op_sel_hi:[1,0,1]
	v_pk_fma_f32 v[66:67], v[66:67], v[80:81], v[110:111] op_sel_hi:[1,0,1]
	v_mul_f32_e32 v80, 0xbfb8aa3b, v76
	v_mul_f32_e32 v81, 0xbfb8aa3b, v77
	v_mul_f32_e32 v84, 0xbfb8aa3b, v78
	v_mul_f32_e32 v85, 0xbfb8aa3b, v79
	v_mul_f32_e32 v86, 0xbfb8aa3b, v72
	v_mul_f32_e32 v87, 0xbfb8aa3b, v73
	v_mul_f32_e32 v88, 0xbfb8aa3b, v74
	v_mul_f32_e32 v89, 0xbfb8aa3b, v75
	v_exp_f32_e32 v80, v80
	v_exp_f32_e32 v81, v81
	v_exp_f32_e32 v84, v84
	v_exp_f32_e32 v85, v85
	v_exp_f32_e32 v86, v86
	v_exp_f32_e32 v87, v87
	v_exp_f32_e32 v88, v88
	v_exp_f32_e32 v89, v89
	v_add_f32_e32 v80, 1.0, v80
	v_add_f32_e32 v81, 1.0, v81
	v_add_f32_e32 v84, 1.0, v84
	v_add_f32_e32 v85, 1.0, v85
	v_add_f32_e32 v86, 1.0, v86
	v_add_f32_e32 v87, 1.0, v87
	v_add_f32_e32 v88, 1.0, v88
	v_add_f32_e32 v89, 1.0, v89
	v_rcp_f32_e32 v80, v80
	v_rcp_f32_e32 v81, v81
	v_rcp_f32_e32 v84, v84
	v_rcp_f32_e32 v85, v85
	v_rcp_f32_e32 v86, v86
	v_rcp_f32_e32 v87, v87
	v_rcp_f32_e32 v88, v88
	v_rcp_f32_e32 v89, v89
	v_pk_mul_f32 v[76:77], v[76:77], v[80:81]
	v_pk_mul_f32 v[78:79], v[78:79], v[84:85]
	v_pk_mul_f32 v[72:73], v[72:73], v[86:87]
	v_pk_mul_f32 v[74:75], v[74:75], v[88:89]
	v_pk_mul_f32 v[68:69], v[68:69], v[76:77]
	v_pk_mul_f32 v[70:71], v[70:71], v[78:79]
	v_pk_mul_f32 v[72:73], v[64:65], v[72:73]
	v_pk_mul_f32 v[74:75], v[66:67], v[74:75]
	v_cvt_pk_f16_f32 v64, v68, v69
	v_cvt_pk_f16_f32 v65, v70, v71
	v_cvt_pk_f16_f32 v66, v72, v73
	v_cvt_pk_f16_f32 v67, v74, v75
	global_store_dwordx4 v[82:83], v[64:67], off
	s_nop 0
	s_nop 0
	v_add_u32_e32 v65, 0x80, v160
	v_mad_i64_i32 v[66:67], s[24:25], v65, s60, v[162:163]
	v_lshl_add_u64 v[66:67], v[66:67], 0, v[166:167]
	v_fmamk_f32 v64, v244, 0x3a800000, v175
	v_rsq_f32_e32 v64, v64
	s_nop 0
	v_pk_fma_f32 v[60:61], v[60:61], v[64:65], v[112:113] op_sel_hi:[1,0,1]
	v_pk_fma_f32 v[62:63], v[62:63], v[64:65], v[114:115] op_sel_hi:[1,0,1]
	v_pk_fma_f32 v[56:57], v[56:57], v[64:65], v[104:105] op_sel_hi:[1,0,1]
	v_pk_fma_f32 v[58:59], v[58:59], v[64:65], v[106:107] op_sel_hi:[1,0,1]
	v_pk_fma_f32 v[52:53], v[52:53], v[64:65], v[116:117] op_sel_hi:[1,0,1]
	v_pk_fma_f32 v[54:55], v[54:55], v[64:65], v[118:119] op_sel_hi:[1,0,1]
	v_pk_fma_f32 v[48:49], v[48:49], v[64:65], v[108:109] op_sel_hi:[1,0,1]
	v_pk_fma_f32 v[50:51], v[50:51], v[64:65], v[110:111] op_sel_hi:[1,0,1]
	v_mul_f32_e32 v64, 0xbfb8aa3b, v60
	v_mul_f32_e32 v65, 0xbfb8aa3b, v61
	v_mul_f32_e32 v68, 0xbfb8aa3b, v62
	v_mul_f32_e32 v69, 0xbfb8aa3b, v63
	v_mul_f32_e32 v70, 0xbfb8aa3b, v56
	v_mul_f32_e32 v71, 0xbfb8aa3b, v57
	v_mul_f32_e32 v72, 0xbfb8aa3b, v58
	v_mul_f32_e32 v73, 0xbfb8aa3b, v59
	v_exp_f32_e32 v64, v64
	v_exp_f32_e32 v65, v65
	v_exp_f32_e32 v68, v68
	v_exp_f32_e32 v69, v69
	v_exp_f32_e32 v70, v70
	v_exp_f32_e32 v71, v71
	v_exp_f32_e32 v72, v72
	v_exp_f32_e32 v73, v73
	v_add_f32_e32 v64, 1.0, v64
	v_add_f32_e32 v65, 1.0, v65
	v_add_f32_e32 v68, 1.0, v68
	v_add_f32_e32 v69, 1.0, v69
	v_add_f32_e32 v70, 1.0, v70
	v_add_f32_e32 v71, 1.0, v71
	v_add_f32_e32 v72, 1.0, v72
	v_add_f32_e32 v73, 1.0, v73
	v_rcp_f32_e32 v64, v64
	v_rcp_f32_e32 v65, v65
	v_rcp_f32_e32 v68, v68
	v_rcp_f32_e32 v69, v69
	v_rcp_f32_e32 v70, v70
	v_rcp_f32_e32 v71, v71
	v_rcp_f32_e32 v72, v72
	v_rcp_f32_e32 v73, v73
	v_pk_mul_f32 v[60:61], v[60:61], v[64:65]
	v_pk_mul_f32 v[62:63], v[62:63], v[68:69]
	v_pk_mul_f32 v[56:57], v[56:57], v[70:71]
	v_pk_mul_f32 v[58:59], v[58:59], v[72:73]
	v_pk_mul_f32 v[52:53], v[52:53], v[60:61]
	v_pk_mul_f32 v[54:55], v[54:55], v[62:63]
	v_pk_mul_f32 v[56:57], v[48:49], v[56:57]
	v_pk_mul_f32 v[58:59], v[50:51], v[58:59]
	v_cvt_pk_f16_f32 v48, v52, v53
	v_cvt_pk_f16_f32 v49, v54, v55
	v_cvt_pk_f16_f32 v50, v56, v57
	v_cvt_pk_f16_f32 v51, v58, v59
	global_store_dwordx4 v[66:67], v[48:51], off
	s_nop 0
	s_nop 0
	v_add_u32_e32 v49, 0x90, v160
	v_mad_i64_i32 v[50:51], s[24:25], v49, s60, v[162:163]
	v_lshl_add_u64 v[50:51], v[50:51], 0, v[166:167]
	v_fmamk_f32 v48, v245, 0x3a800000, v175
	v_rsq_f32_e32 v48, v48
	s_nop 0
	v_pk_fma_f32 v[44:45], v[44:45], v[48:49], v[112:113] op_sel_hi:[1,0,1]
	v_pk_fma_f32 v[46:47], v[46:47], v[48:49], v[114:115] op_sel_hi:[1,0,1]
	v_pk_fma_f32 v[40:41], v[40:41], v[48:49], v[104:105] op_sel_hi:[1,0,1]
	v_pk_fma_f32 v[42:43], v[42:43], v[48:49], v[106:107] op_sel_hi:[1,0,1]
	v_pk_fma_f32 v[36:37], v[36:37], v[48:49], v[116:117] op_sel_hi:[1,0,1]
	v_pk_fma_f32 v[38:39], v[38:39], v[48:49], v[118:119] op_sel_hi:[1,0,1]
	v_pk_fma_f32 v[32:33], v[32:33], v[48:49], v[108:109] op_sel_hi:[1,0,1]
	v_pk_fma_f32 v[34:35], v[34:35], v[48:49], v[110:111] op_sel_hi:[1,0,1]
	v_mul_f32_e32 v48, 0xbfb8aa3b, v44
	v_mul_f32_e32 v49, 0xbfb8aa3b, v45
	v_mul_f32_e32 v52, 0xbfb8aa3b, v46
	v_mul_f32_e32 v53, 0xbfb8aa3b, v47
	v_mul_f32_e32 v54, 0xbfb8aa3b, v40
	v_mul_f32_e32 v55, 0xbfb8aa3b, v41
	v_mul_f32_e32 v56, 0xbfb8aa3b, v42
	v_mul_f32_e32 v57, 0xbfb8aa3b, v43
	v_exp_f32_e32 v48, v48
	v_exp_f32_e32 v49, v49
	v_exp_f32_e32 v52, v52
	v_exp_f32_e32 v53, v53
	v_exp_f32_e32 v54, v54
	v_exp_f32_e32 v55, v55
	v_exp_f32_e32 v56, v56
	v_exp_f32_e32 v57, v57
	v_add_f32_e32 v48, 1.0, v48
	v_add_f32_e32 v49, 1.0, v49
	v_add_f32_e32 v52, 1.0, v52
	v_add_f32_e32 v53, 1.0, v53
	v_add_f32_e32 v54, 1.0, v54
	v_add_f32_e32 v55, 1.0, v55
	v_add_f32_e32 v56, 1.0, v56
	v_add_f32_e32 v57, 1.0, v57
	v_rcp_f32_e32 v48, v48
	v_rcp_f32_e32 v49, v49
	v_rcp_f32_e32 v52, v52
	v_rcp_f32_e32 v53, v53
	v_rcp_f32_e32 v54, v54
	v_rcp_f32_e32 v55, v55
	v_rcp_f32_e32 v56, v56
	v_rcp_f32_e32 v57, v57
	v_pk_mul_f32 v[44:45], v[44:45], v[48:49]
	v_pk_mul_f32 v[46:47], v[46:47], v[52:53]
	v_pk_mul_f32 v[40:41], v[40:41], v[54:55]
	v_pk_mul_f32 v[42:43], v[42:43], v[56:57]
	v_pk_mul_f32 v[36:37], v[36:37], v[44:45]
	v_pk_mul_f32 v[38:39], v[38:39], v[46:47]
	v_pk_mul_f32 v[40:41], v[32:33], v[40:41]
	v_pk_mul_f32 v[42:43], v[34:35], v[42:43]
	v_cvt_pk_f16_f32 v32, v36, v37
	v_cvt_pk_f16_f32 v33, v38, v39
	v_cvt_pk_f16_f32 v34, v40, v41
	v_cvt_pk_f16_f32 v35, v42, v43
	global_store_dwordx4 v[50:51], v[32:35], off
	s_nop 0
	s_nop 0
	v_add_u32_e32 v33, 0xa0, v160
	v_mad_i64_i32 v[34:35], s[24:25], v33, s60, v[162:163]
	v_lshl_add_u64 v[34:35], v[34:35], 0, v[166:167]
	v_fmamk_f32 v32, v246, 0x3a800000, v175
	v_rsq_f32_e32 v32, v32
	s_nop 0
	v_pk_fma_f32 v[28:29], v[28:29], v[32:33], v[112:113] op_sel_hi:[1,0,1]
	v_pk_fma_f32 v[30:31], v[30:31], v[32:33], v[114:115] op_sel_hi:[1,0,1]
	v_pk_fma_f32 v[24:25], v[24:25], v[32:33], v[104:105] op_sel_hi:[1,0,1]
	v_pk_fma_f32 v[26:27], v[26:27], v[32:33], v[106:107] op_sel_hi:[1,0,1]
	v_pk_fma_f32 v[20:21], v[20:21], v[32:33], v[116:117] op_sel_hi:[1,0,1]
	v_pk_fma_f32 v[22:23], v[22:23], v[32:33], v[118:119] op_sel_hi:[1,0,1]
	v_pk_fma_f32 v[16:17], v[16:17], v[32:33], v[108:109] op_sel_hi:[1,0,1]
	v_pk_fma_f32 v[18:19], v[18:19], v[32:33], v[110:111] op_sel_hi:[1,0,1]
	v_mul_f32_e32 v32, 0xbfb8aa3b, v28
	v_mul_f32_e32 v33, 0xbfb8aa3b, v29
	v_mul_f32_e32 v36, 0xbfb8aa3b, v30
	v_mul_f32_e32 v37, 0xbfb8aa3b, v31
	v_mul_f32_e32 v38, 0xbfb8aa3b, v24
	v_mul_f32_e32 v39, 0xbfb8aa3b, v25
	v_mul_f32_e32 v40, 0xbfb8aa3b, v26
	v_mul_f32_e32 v41, 0xbfb8aa3b, v27
	v_exp_f32_e32 v32, v32
	v_exp_f32_e32 v33, v33
	v_exp_f32_e32 v36, v36
	v_exp_f32_e32 v37, v37
	v_exp_f32_e32 v38, v38
	v_exp_f32_e32 v39, v39
	v_exp_f32_e32 v40, v40
	v_exp_f32_e32 v41, v41
	v_add_f32_e32 v32, 1.0, v32
	v_add_f32_e32 v33, 1.0, v33
	v_add_f32_e32 v36, 1.0, v36
	v_add_f32_e32 v37, 1.0, v37
	v_add_f32_e32 v38, 1.0, v38
	v_add_f32_e32 v39, 1.0, v39
	v_add_f32_e32 v40, 1.0, v40
	v_add_f32_e32 v41, 1.0, v41
	v_rcp_f32_e32 v32, v32
	v_rcp_f32_e32 v33, v33
	v_rcp_f32_e32 v36, v36
	v_rcp_f32_e32 v37, v37
	v_rcp_f32_e32 v38, v38
	v_rcp_f32_e32 v39, v39
	v_rcp_f32_e32 v40, v40
	v_rcp_f32_e32 v41, v41
	v_pk_mul_f32 v[28:29], v[28:29], v[32:33]
	v_pk_mul_f32 v[30:31], v[30:31], v[36:37]
	v_pk_mul_f32 v[24:25], v[24:25], v[38:39]
	v_pk_mul_f32 v[26:27], v[26:27], v[40:41]
	v_pk_mul_f32 v[20:21], v[20:21], v[28:29]
	v_pk_mul_f32 v[22:23], v[22:23], v[30:31]
	v_pk_mul_f32 v[24:25], v[16:17], v[24:25]
	v_pk_mul_f32 v[26:27], v[18:19], v[26:27]
	v_cvt_pk_f16_f32 v16, v20, v21
	v_cvt_pk_f16_f32 v17, v22, v23
	v_cvt_pk_f16_f32 v18, v24, v25
	v_cvt_pk_f16_f32 v19, v26, v27
	global_store_dwordx4 v[34:35], v[16:19], off
	s_nop 0
	s_nop 0
	v_add_u32_e32 v17, 0xb0, v160
	v_mad_i64_i32 v[18:19], s[24:25], v17, s60, v[162:163]
	v_lshl_add_u64 v[18:19], v[18:19], 0, v[166:167]
	v_fmamk_f32 v16, v247, 0x3a800000, v175
	v_rsq_f32_e32 v16, v16
	s_nop 0
	v_pk_fma_f32 v[12:13], v[12:13], v[16:17], v[112:113] op_sel_hi:[1,0,1]
	v_pk_fma_f32 v[14:15], v[14:15], v[16:17], v[114:115] op_sel_hi:[1,0,1]
	v_pk_fma_f32 v[8:9], v[8:9], v[16:17], v[104:105] op_sel_hi:[1,0,1]
	v_pk_fma_f32 v[10:11], v[10:11], v[16:17], v[106:107] op_sel_hi:[1,0,1]
	v_pk_fma_f32 v[4:5], v[4:5], v[16:17], v[116:117] op_sel_hi:[1,0,1]
	v_pk_fma_f32 v[6:7], v[6:7], v[16:17], v[118:119] op_sel_hi:[1,0,1]
	v_pk_fma_f32 v[0:1], v[0:1], v[16:17], v[108:109] op_sel_hi:[1,0,1]
	v_pk_fma_f32 v[2:3], v[2:3], v[16:17], v[110:111] op_sel_hi:[1,0,1]
	v_mul_f32_e32 v16, 0xbfb8aa3b, v12
	v_mul_f32_e32 v17, 0xbfb8aa3b, v13
	v_mul_f32_e32 v20, 0xbfb8aa3b, v14
	v_mul_f32_e32 v21, 0xbfb8aa3b, v15
	v_mul_f32_e32 v22, 0xbfb8aa3b, v8
	v_mul_f32_e32 v23, 0xbfb8aa3b, v9
	v_mul_f32_e32 v24, 0xbfb8aa3b, v10
	v_mul_f32_e32 v25, 0xbfb8aa3b, v11
	v_exp_f32_e32 v16, v16
	v_exp_f32_e32 v17, v17
	v_exp_f32_e32 v20, v20
	v_exp_f32_e32 v21, v21
	v_exp_f32_e32 v22, v22
	v_exp_f32_e32 v23, v23
	v_exp_f32_e32 v24, v24
	v_exp_f32_e32 v25, v25
	v_add_f32_e32 v16, 1.0, v16
	v_add_f32_e32 v17, 1.0, v17
	v_add_f32_e32 v20, 1.0, v20
	v_add_f32_e32 v21, 1.0, v21
	v_add_f32_e32 v22, 1.0, v22
	v_add_f32_e32 v23, 1.0, v23
	v_add_f32_e32 v24, 1.0, v24
	v_add_f32_e32 v25, 1.0, v25
	v_rcp_f32_e32 v16, v16
	v_rcp_f32_e32 v17, v17
	v_rcp_f32_e32 v20, v20
	v_rcp_f32_e32 v21, v21
	v_rcp_f32_e32 v22, v22
	v_rcp_f32_e32 v23, v23
	v_rcp_f32_e32 v24, v24
	v_rcp_f32_e32 v25, v25
	v_pk_mul_f32 v[12:13], v[12:13], v[16:17]
	v_pk_mul_f32 v[14:15], v[14:15], v[20:21]
	v_pk_mul_f32 v[8:9], v[8:9], v[22:23]
	v_pk_mul_f32 v[10:11], v[10:11], v[24:25]
	v_pk_mul_f32 v[4:5], v[4:5], v[12:13]
	v_pk_mul_f32 v[6:7], v[6:7], v[14:15]
	v_pk_mul_f32 v[8:9], v[0:1], v[8:9]
	v_pk_mul_f32 v[10:11], v[2:3], v[10:11]
	v_cvt_pk_f16_f32 v0, v4, v5
	v_cvt_pk_f16_f32 v1, v6, v7
	v_cvt_pk_f16_f32 v2, v8, v9
	v_cvt_pk_f16_f32 v3, v10, v11
	global_store_dwordx4 v[18:19], v[0:3], off
	s_cbranch_vccnz .LBB0_865
	s_andn2_b64 vcc, exec, s[4:5]
	s_cbranch_vccnz .LBB0_864
	s_barrier
	s_branch .LBB0_864

.LBB0_1588:
	s_cmp_lt_i32 s22, 64
	s_cselect_b32 s15, s57, 0x2c00
	s_cmp_gt_i32 s22, 31
	s_cselect_b32 s15, s15, 0
	v_lshl_add_u32 v160, s22, 8, v168
	s_lshl_b32 s15, s15, 2
	s_add_u32 s15, s50, s15
	v_ashrrev_i32_e32 v161, 31, v160
	s_addc_u32 s17, s51, 0
	s_lshl_b32 s24, s59, 8
	v_lshl_add_u64 v[164:165], v[160:161], 2, s[6:7]
	s_ashr_i32 s25, s24, 31
	global_load_dword v161, v[164:165], off
	global_load_dword v241, v[164:165], off offset:64
	global_load_dword v242, v[164:165], off offset:128
	global_load_dword v243, v[164:165], off offset:192
	global_load_dword v244, v[164:165], off offset:512
	global_load_dword v245, v[164:165], off offset:576
	global_load_dword v246, v[164:165], off offset:640
	global_load_dword v247, v[164:165], off offset:704
	s_lshl_b64 s[24:25], s[24:25], 2
	s_add_u32 s15, s15, s24
	s_addc_u32 s17, s17, s25
	s_add_u32 s24, s15, s58
	s_addc_u32 s25, s17, 0
	global_load_dwordx4 v[112:115], v174, s[24:25]
	global_load_dwordx4 v[116:119], v174, s[24:25] offset:512
	global_load_dwordx4 v[104:107], v174, s[24:25] offset:16
	global_load_dwordx4 v[108:111], v174, s[24:25] offset:528
	v_or_b32_e32 v180, 16, v160
	v_ashrrev_i32_e32 v181, 31, v180
	v_lshl_add_u64 v[184:185], v[180:181], 2, s[6:7]
	v_lshl_or_b32 v166, s59, 7, v170
	v_mov_b64_e32 v[162:163], s[36:37]
	v_ashrrev_i32_e32 v167, 31, v166
	v_mad_i64_i32 v[178:179], s[24:25], v160, s57, v[162:163]
	v_lshlrev_b64 v[166:167], 1, v[166:167]
	v_lshl_add_u64 v[178:179], v[178:179], 0, v[166:167]
	s_andn2_b64 vcc, exec, s[2:3]
	s_mov_b64 s[2:3], -1
	s_waitcnt vmcnt(0)
	v_fmamk_f32 v161, v161, 0x3a800000, v175
	v_rsq_f32_e32 v182, v161
	s_nop 0
	v_pk_fma_f32 v[140:141], v[140:141], v[182:183], v[112:113] op_sel_hi:[1,0,1]
	v_pk_fma_f32 v[142:143], v[142:143], v[182:183], v[114:115] op_sel_hi:[1,0,1]
	v_pk_fma_f32 v[136:137], v[136:137], v[182:183], v[104:105] op_sel_hi:[1,0,1]
	v_pk_fma_f32 v[138:139], v[138:139], v[182:183], v[106:107] op_sel_hi:[1,0,1]
	v_pk_fma_f32 v[132:133], v[132:133], v[182:183], v[116:117] op_sel_hi:[1,0,1]
	v_pk_fma_f32 v[134:135], v[134:135], v[182:183], v[118:119] op_sel_hi:[1,0,1]
	v_pk_fma_f32 v[128:129], v[128:129], v[182:183], v[108:109] op_sel_hi:[1,0,1]
	v_pk_fma_f32 v[130:131], v[130:131], v[182:183], v[110:111] op_sel_hi:[1,0,1]
	v_mul_f32_e32 v161, 0xbfb8aa3b, v140
	v_mul_f32_e32 v177, 0xbfb8aa3b, v141
	v_mul_f32_e32 v181, 0xbfb8aa3b, v142
	v_mul_f32_e32 v182, 0xbfb8aa3b, v143
	v_mul_f32_e32 v183, 0xbfb8aa3b, v136
	v_mul_f32_e32 v186, 0xbfb8aa3b, v137
	v_mul_f32_e32 v187, 0xbfb8aa3b, v138
	v_mul_f32_e32 v188, 0xbfb8aa3b, v139
	v_exp_f32_e32 v161, v161
	v_exp_f32_e32 v177, v177
	v_exp_f32_e32 v181, v181
	v_exp_f32_e32 v182, v182
	v_exp_f32_e32 v183, v183
	v_exp_f32_e32 v186, v186
	v_exp_f32_e32 v187, v187
	v_exp_f32_e32 v188, v188
	v_add_f32_e32 v161, 1.0, v161
	v_add_f32_e32 v177, 1.0, v177
	v_add_f32_e32 v181, 1.0, v181
	v_add_f32_e32 v189, 1.0, v182
	v_add_f32_e32 v190, 1.0, v183
	v_add_f32_e32 v191, 1.0, v186
	v_add_f32_e32 v192, 1.0, v187
	v_add_f32_e32 v193, 1.0, v188
	v_rcp_f32_e32 v182, v161
	v_rcp_f32_e32 v183, v177
	v_rcp_f32_e32 v186, v181
	v_rcp_f32_e32 v187, v189
	v_rcp_f32_e32 v188, v190
	v_rcp_f32_e32 v189, v191
	v_rcp_f32_e32 v190, v192
	v_rcp_f32_e32 v191, v193
	v_pk_mul_f32 v[140:141], v[140:141], v[182:183]
	v_pk_mul_f32 v[142:143], v[142:143], v[186:187]
	v_pk_mul_f32 v[136:137], v[136:137], v[188:189]
	v_pk_mul_f32 v[138:139], v[138:139], v[190:191]
	v_pk_mul_f32 v[132:133], v[132:133], v[140:141]
	v_pk_mul_f32 v[134:135], v[134:135], v[142:143]
	v_pk_mul_f32 v[136:137], v[128:129], v[136:137]
	v_pk_mul_f32 v[138:139], v[130:131], v[138:139]
	v_cvt_pk_f16_f32 v128, v132, v133
	v_cvt_pk_f16_f32 v129, v134, v135
	v_cvt_pk_f16_f32 v130, v136, v137
	v_cvt_pk_f16_f32 v131, v138, v139
	global_store_dwordx4 v[178:179], v[128:131], off
	s_nop 0
	s_nop 0
	v_or_b32_e32 v128, 32, v160
	v_mad_i64_i32 v[130:131], s[24:25], v180, s57, v[162:163]
	v_lshl_add_u64 v[130:131], v[130:131], 0, v[166:167]
	v_fmamk_f32 v129, v241, 0x3a800000, v175
	v_rsq_f32_e32 v132, v129
	v_ashrrev_i32_e32 v129, 31, v128
	v_lshl_add_u64 v[134:135], v[128:129], 2, s[6:7]
	v_pk_fma_f32 v[124:125], v[124:125], v[132:133], v[112:113] op_sel_hi:[1,0,1]
	v_pk_fma_f32 v[126:127], v[126:127], v[132:133], v[114:115] op_sel_hi:[1,0,1]
	v_pk_fma_f32 v[120:121], v[120:121], v[132:133], v[104:105] op_sel_hi:[1,0,1]
	v_pk_fma_f32 v[122:123], v[122:123], v[132:133], v[106:107] op_sel_hi:[1,0,1]
	v_pk_fma_f32 v[100:101], v[100:101], v[132:133], v[116:117] op_sel_hi:[1,0,1]
	v_pk_fma_f32 v[102:103], v[102:103], v[132:133], v[118:119] op_sel_hi:[1,0,1]
	v_pk_fma_f32 v[96:97], v[96:97], v[132:133], v[108:109] op_sel_hi:[1,0,1]
	v_pk_fma_f32 v[98:99], v[98:99], v[132:133], v[110:111] op_sel_hi:[1,0,1]
	v_mul_f32_e32 v129, 0xbfb8aa3b, v124
	v_mul_f32_e32 v132, 0xbfb8aa3b, v125
	v_mul_f32_e32 v133, 0xbfb8aa3b, v126
	v_mul_f32_e32 v136, 0xbfb8aa3b, v127
	v_mul_f32_e32 v137, 0xbfb8aa3b, v120
	v_mul_f32_e32 v138, 0xbfb8aa3b, v121
	v_mul_f32_e32 v139, 0xbfb8aa3b, v122
	v_mul_f32_e32 v140, 0xbfb8aa3b, v123
	v_exp_f32_e32 v129, v129
	v_exp_f32_e32 v132, v132
	v_exp_f32_e32 v133, v133
	v_exp_f32_e32 v136, v136
	v_exp_f32_e32 v137, v137
	v_exp_f32_e32 v138, v138
	v_exp_f32_e32 v139, v139
	v_exp_f32_e32 v140, v140
	v_add_f32_e32 v129, 1.0, v129
	v_add_f32_e32 v141, 1.0, v132
	v_add_f32_e32 v142, 1.0, v133
	v_add_f32_e32 v143, 1.0, v136
	v_add_f32_e32 v161, 1.0, v137
	v_add_f32_e32 v177, 1.0, v138
	v_add_f32_e32 v178, 1.0, v139
	v_add_f32_e32 v179, 1.0, v140
	v_rcp_f32_e32 v132, v129
	v_rcp_f32_e32 v133, v141
	v_rcp_f32_e32 v136, v142
	v_rcp_f32_e32 v137, v143
	v_rcp_f32_e32 v138, v161
	v_rcp_f32_e32 v139, v177
	v_rcp_f32_e32 v140, v178
	v_rcp_f32_e32 v141, v179
	v_pk_mul_f32 v[124:125], v[124:125], v[132:133]
	v_pk_mul_f32 v[126:127], v[126:127], v[136:137]
	v_pk_mul_f32 v[120:121], v[120:121], v[138:139]
	v_pk_mul_f32 v[122:123], v[122:123], v[140:141]
	v_pk_mul_f32 v[100:101], v[100:101], v[124:125]
	v_pk_mul_f32 v[102:103], v[102:103], v[126:127]
	v_pk_mul_f32 v[120:121], v[96:97], v[120:121]
	v_pk_mul_f32 v[122:123], v[98:99], v[122:123]
	v_cvt_pk_f16_f32 v96, v100, v101
	v_cvt_pk_f16_f32 v97, v102, v103
	v_cvt_pk_f16_f32 v98, v120, v121
	v_cvt_pk_f16_f32 v99, v122, v123
	global_store_dwordx4 v[130:131], v[96:99], off
	s_nop 0
	s_nop 0
	v_or_b32_e32 v96, 48, v160
	v_mad_i64_i32 v[98:99], s[24:25], v128, s57, v[162:163]
	v_lshl_add_u64 v[98:99], v[98:99], 0, v[166:167]
	v_fmamk_f32 v97, v242, 0x3a800000, v175
	v_rsq_f32_e32 v100, v97
	v_ashrrev_i32_e32 v97, 31, v96
	v_lshl_add_u64 v[102:103], v[96:97], 2, s[6:7]
	v_pk_fma_f32 v[92:93], v[92:93], v[100:101], v[112:113] op_sel_hi:[1,0,1]
	v_pk_fma_f32 v[94:95], v[94:95], v[100:101], v[114:115] op_sel_hi:[1,0,1]
	v_pk_fma_f32 v[88:89], v[88:89], v[100:101], v[104:105] op_sel_hi:[1,0,1]
	v_pk_fma_f32 v[90:91], v[90:91], v[100:101], v[106:107] op_sel_hi:[1,0,1]
	v_pk_fma_f32 v[84:85], v[84:85], v[100:101], v[116:117] op_sel_hi:[1,0,1]
	v_pk_fma_f32 v[86:87], v[86:87], v[100:101], v[118:119] op_sel_hi:[1,0,1]
	v_pk_fma_f32 v[80:81], v[80:81], v[100:101], v[108:109] op_sel_hi:[1,0,1]
	v_pk_fma_f32 v[82:83], v[82:83], v[100:101], v[110:111] op_sel_hi:[1,0,1]
	v_mul_f32_e32 v97, 0xbfb8aa3b, v92
	v_mul_f32_e32 v100, 0xbfb8aa3b, v93
	v_mul_f32_e32 v101, 0xbfb8aa3b, v94
	v_mul_f32_e32 v120, 0xbfb8aa3b, v95
	v_mul_f32_e32 v121, 0xbfb8aa3b, v88
	v_mul_f32_e32 v122, 0xbfb8aa3b, v89
	v_mul_f32_e32 v123, 0xbfb8aa3b, v90
	v_mul_f32_e32 v124, 0xbfb8aa3b, v91
	v_exp_f32_e32 v97, v97
	v_exp_f32_e32 v100, v100
	v_exp_f32_e32 v101, v101
	v_exp_f32_e32 v120, v120
	v_exp_f32_e32 v121, v121
	v_exp_f32_e32 v122, v122
	v_exp_f32_e32 v123, v123
	v_exp_f32_e32 v124, v124
	v_add_f32_e32 v97, 1.0, v97
	v_add_f32_e32 v125, 1.0, v100
	v_add_f32_e32 v126, 1.0, v101
	v_add_f32_e32 v127, 1.0, v120
	v_add_f32_e32 v128, 1.0, v121
	v_add_f32_e32 v129, 1.0, v122
	v_add_f32_e32 v130, 1.0, v123
	v_add_f32_e32 v131, 1.0, v124
	v_rcp_f32_e32 v100, v97
	v_rcp_f32_e32 v101, v125
	v_rcp_f32_e32 v120, v126
	v_rcp_f32_e32 v121, v127
	v_rcp_f32_e32 v122, v128
	v_rcp_f32_e32 v123, v129
	v_rcp_f32_e32 v124, v130
	v_rcp_f32_e32 v125, v131
	v_pk_mul_f32 v[92:93], v[92:93], v[100:101]
	v_pk_mul_f32 v[94:95], v[94:95], v[120:121]
	v_pk_mul_f32 v[88:89], v[88:89], v[122:123]
	v_pk_mul_f32 v[90:91], v[90:91], v[124:125]
	v_pk_mul_f32 v[84:85], v[84:85], v[92:93]
	v_pk_mul_f32 v[86:87], v[86:87], v[94:95]
	v_pk_mul_f32 v[88:89], v[80:81], v[88:89]
	v_pk_mul_f32 v[90:91], v[82:83], v[90:91]
	v_cvt_pk_f16_f32 v80, v84, v85
	v_cvt_pk_f16_f32 v81, v86, v87
	v_cvt_pk_f16_f32 v82, v88, v89
	v_cvt_pk_f16_f32 v83, v90, v91
	global_store_dwordx4 v[98:99], v[80:83], off
	s_nop 0
	s_nop 0
	v_mad_i64_i32 v[82:83], s[24:25], v96, s57, v[162:163]
	v_lshl_add_u64 v[82:83], v[82:83], 0, v[166:167]
	v_fmamk_f32 v80, v243, 0x3a800000, v175
	v_rsq_f32_e32 v80, v80
	s_nop 0
	v_pk_fma_f32 v[76:77], v[76:77], v[80:81], v[112:113] op_sel_hi:[1,0,1]
	v_pk_fma_f32 v[78:79], v[78:79], v[80:81], v[114:115] op_sel_hi:[1,0,1]
	v_pk_fma_f32 v[72:73], v[72:73], v[80:81], v[104:105] op_sel_hi:[1,0,1]
	v_pk_fma_f32 v[74:75], v[74:75], v[80:81], v[106:107] op_sel_hi:[1,0,1]
	v_pk_fma_f32 v[68:69], v[68:69], v[80:81], v[116:117] op_sel_hi:[1,0,1]
	v_pk_fma_f32 v[70:71], v[70:71], v[80:81], v[118:119] op_sel_hi:[1,0,1]
	v_pk_fma_f32 v[64:65], v[64:65], v[80:81], v[108:109] op_sel_hi:[1,0,1]
	v_pk_fma_f32 v[66:67], v[66:67], v[80:81], v[110:111] op_sel_hi:[1,0,1]
	v_mul_f32_e32 v80, 0xbfb8aa3b, v76
	v_mul_f32_e32 v81, 0xbfb8aa3b, v77
	v_mul_f32_e32 v84, 0xbfb8aa3b, v78
	v_mul_f32_e32 v85, 0xbfb8aa3b, v79
	v_mul_f32_e32 v86, 0xbfb8aa3b, v72
	v_mul_f32_e32 v87, 0xbfb8aa3b, v73
	v_mul_f32_e32 v88, 0xbfb8aa3b, v74
	v_mul_f32_e32 v89, 0xbfb8aa3b, v75
	v_exp_f32_e32 v80, v80
	v_exp_f32_e32 v81, v81
	v_exp_f32_e32 v84, v84
	v_exp_f32_e32 v85, v85
	v_exp_f32_e32 v86, v86
	v_exp_f32_e32 v87, v87
	v_exp_f32_e32 v88, v88
	v_exp_f32_e32 v89, v89
	v_add_f32_e32 v80, 1.0, v80
	v_add_f32_e32 v81, 1.0, v81
	v_add_f32_e32 v84, 1.0, v84
	v_add_f32_e32 v85, 1.0, v85
	v_add_f32_e32 v86, 1.0, v86
	v_add_f32_e32 v87, 1.0, v87
	v_add_f32_e32 v88, 1.0, v88
	v_add_f32_e32 v89, 1.0, v89
	v_rcp_f32_e32 v80, v80
	v_rcp_f32_e32 v81, v81
	v_rcp_f32_e32 v84, v84
	v_rcp_f32_e32 v85, v85
	v_rcp_f32_e32 v86, v86
	v_rcp_f32_e32 v87, v87
	v_rcp_f32_e32 v88, v88
	v_rcp_f32_e32 v89, v89
	v_pk_mul_f32 v[76:77], v[76:77], v[80:81]
	v_pk_mul_f32 v[78:79], v[78:79], v[84:85]
	v_pk_mul_f32 v[72:73], v[72:73], v[86:87]
	v_pk_mul_f32 v[74:75], v[74:75], v[88:89]
	v_pk_mul_f32 v[68:69], v[68:69], v[76:77]
	v_pk_mul_f32 v[70:71], v[70:71], v[78:79]
	v_pk_mul_f32 v[72:73], v[64:65], v[72:73]
	v_pk_mul_f32 v[74:75], v[66:67], v[74:75]
	v_cvt_pk_f16_f32 v64, v68, v69
	v_cvt_pk_f16_f32 v65, v70, v71
	v_cvt_pk_f16_f32 v66, v72, v73
	v_cvt_pk_f16_f32 v67, v74, v75
	global_store_dwordx4 v[82:83], v[64:67], off
	s_nop 0
	s_nop 0
	v_add_u32_e32 v65, 0x80, v160
	v_mad_i64_i32 v[66:67], s[24:25], v65, s57, v[162:163]
	v_lshl_add_u64 v[66:67], v[66:67], 0, v[166:167]
	v_fmamk_f32 v64, v244, 0x3a800000, v175
	v_rsq_f32_e32 v64, v64
	s_nop 0
	v_pk_fma_f32 v[60:61], v[60:61], v[64:65], v[112:113] op_sel_hi:[1,0,1]
	v_pk_fma_f32 v[62:63], v[62:63], v[64:65], v[114:115] op_sel_hi:[1,0,1]
	v_pk_fma_f32 v[56:57], v[56:57], v[64:65], v[104:105] op_sel_hi:[1,0,1]
	v_pk_fma_f32 v[58:59], v[58:59], v[64:65], v[106:107] op_sel_hi:[1,0,1]
	v_pk_fma_f32 v[52:53], v[52:53], v[64:65], v[116:117] op_sel_hi:[1,0,1]
	v_pk_fma_f32 v[54:55], v[54:55], v[64:65], v[118:119] op_sel_hi:[1,0,1]
	v_pk_fma_f32 v[48:49], v[48:49], v[64:65], v[108:109] op_sel_hi:[1,0,1]
	v_pk_fma_f32 v[50:51], v[50:51], v[64:65], v[110:111] op_sel_hi:[1,0,1]
	v_mul_f32_e32 v64, 0xbfb8aa3b, v60
	v_mul_f32_e32 v65, 0xbfb8aa3b, v61
	v_mul_f32_e32 v68, 0xbfb8aa3b, v62
	v_mul_f32_e32 v69, 0xbfb8aa3b, v63
	v_mul_f32_e32 v70, 0xbfb8aa3b, v56
	v_mul_f32_e32 v71, 0xbfb8aa3b, v57
	v_mul_f32_e32 v72, 0xbfb8aa3b, v58
	v_mul_f32_e32 v73, 0xbfb8aa3b, v59
	v_exp_f32_e32 v64, v64
	v_exp_f32_e32 v65, v65
	v_exp_f32_e32 v68, v68
	v_exp_f32_e32 v69, v69
	v_exp_f32_e32 v70, v70
	v_exp_f32_e32 v71, v71
	v_exp_f32_e32 v72, v72
	v_exp_f32_e32 v73, v73
	v_add_f32_e32 v64, 1.0, v64
	v_add_f32_e32 v65, 1.0, v65
	v_add_f32_e32 v68, 1.0, v68
	v_add_f32_e32 v69, 1.0, v69
	v_add_f32_e32 v70, 1.0, v70
	v_add_f32_e32 v71, 1.0, v71
	v_add_f32_e32 v72, 1.0, v72
	v_add_f32_e32 v73, 1.0, v73
	v_rcp_f32_e32 v64, v64
	v_rcp_f32_e32 v65, v65
	v_rcp_f32_e32 v68, v68
	v_rcp_f32_e32 v69, v69
	v_rcp_f32_e32 v70, v70
	v_rcp_f32_e32 v71, v71
	v_rcp_f32_e32 v72, v72
	v_rcp_f32_e32 v73, v73
	v_pk_mul_f32 v[60:61], v[60:61], v[64:65]
	v_pk_mul_f32 v[62:63], v[62:63], v[68:69]
	v_pk_mul_f32 v[56:57], v[56:57], v[70:71]
	v_pk_mul_f32 v[58:59], v[58:59], v[72:73]
	v_pk_mul_f32 v[52:53], v[52:53], v[60:61]
	v_pk_mul_f32 v[54:55], v[54:55], v[62:63]
	v_pk_mul_f32 v[56:57], v[48:49], v[56:57]
	v_pk_mul_f32 v[58:59], v[50:51], v[58:59]
	v_cvt_pk_f16_f32 v48, v52, v53
	v_cvt_pk_f16_f32 v49, v54, v55
	v_cvt_pk_f16_f32 v50, v56, v57
	v_cvt_pk_f16_f32 v51, v58, v59
	global_store_dwordx4 v[66:67], v[48:51], off
	s_nop 0
	s_nop 0
	v_add_u32_e32 v49, 0x90, v160
	v_mad_i64_i32 v[50:51], s[24:25], v49, s57, v[162:163]
	v_lshl_add_u64 v[50:51], v[50:51], 0, v[166:167]
	v_fmamk_f32 v48, v245, 0x3a800000, v175
	v_rsq_f32_e32 v48, v48
	s_nop 0
	v_pk_fma_f32 v[44:45], v[44:45], v[48:49], v[112:113] op_sel_hi:[1,0,1]
	v_pk_fma_f32 v[46:47], v[46:47], v[48:49], v[114:115] op_sel_hi:[1,0,1]
	v_pk_fma_f32 v[40:41], v[40:41], v[48:49], v[104:105] op_sel_hi:[1,0,1]
	v_pk_fma_f32 v[42:43], v[42:43], v[48:49], v[106:107] op_sel_hi:[1,0,1]
	v_pk_fma_f32 v[36:37], v[36:37], v[48:49], v[116:117] op_sel_hi:[1,0,1]
	v_pk_fma_f32 v[38:39], v[38:39], v[48:49], v[118:119] op_sel_hi:[1,0,1]
	v_pk_fma_f32 v[32:33], v[32:33], v[48:49], v[108:109] op_sel_hi:[1,0,1]
	v_pk_fma_f32 v[34:35], v[34:35], v[48:49], v[110:111] op_sel_hi:[1,0,1]
	v_mul_f32_e32 v48, 0xbfb8aa3b, v44
	v_mul_f32_e32 v49, 0xbfb8aa3b, v45
	v_mul_f32_e32 v52, 0xbfb8aa3b, v46
	v_mul_f32_e32 v53, 0xbfb8aa3b, v47
	v_mul_f32_e32 v54, 0xbfb8aa3b, v40
	v_mul_f32_e32 v55, 0xbfb8aa3b, v41
	v_mul_f32_e32 v56, 0xbfb8aa3b, v42
	v_mul_f32_e32 v57, 0xbfb8aa3b, v43
	v_exp_f32_e32 v48, v48
	v_exp_f32_e32 v49, v49
	v_exp_f32_e32 v52, v52
	v_exp_f32_e32 v53, v53
	v_exp_f32_e32 v54, v54
	v_exp_f32_e32 v55, v55
	v_exp_f32_e32 v56, v56
	v_exp_f32_e32 v57, v57
	v_add_f32_e32 v48, 1.0, v48
	v_add_f32_e32 v49, 1.0, v49
	v_add_f32_e32 v52, 1.0, v52
	v_add_f32_e32 v53, 1.0, v53
	v_add_f32_e32 v54, 1.0, v54
	v_add_f32_e32 v55, 1.0, v55
	v_add_f32_e32 v56, 1.0, v56
	v_add_f32_e32 v57, 1.0, v57
	v_rcp_f32_e32 v48, v48
	v_rcp_f32_e32 v49, v49
	v_rcp_f32_e32 v52, v52
	v_rcp_f32_e32 v53, v53
	v_rcp_f32_e32 v54, v54
	v_rcp_f32_e32 v55, v55
	v_rcp_f32_e32 v56, v56
	v_rcp_f32_e32 v57, v57
	v_pk_mul_f32 v[44:45], v[44:45], v[48:49]
	v_pk_mul_f32 v[46:47], v[46:47], v[52:53]
	v_pk_mul_f32 v[40:41], v[40:41], v[54:55]
	v_pk_mul_f32 v[42:43], v[42:43], v[56:57]
	v_pk_mul_f32 v[36:37], v[36:37], v[44:45]
	v_pk_mul_f32 v[38:39], v[38:39], v[46:47]
	v_pk_mul_f32 v[40:41], v[32:33], v[40:41]
	v_pk_mul_f32 v[42:43], v[34:35], v[42:43]
	v_cvt_pk_f16_f32 v32, v36, v37
	v_cvt_pk_f16_f32 v33, v38, v39
	v_cvt_pk_f16_f32 v34, v40, v41
	v_cvt_pk_f16_f32 v35, v42, v43
	global_store_dwordx4 v[50:51], v[32:35], off
	s_nop 0
	s_nop 0
	v_add_u32_e32 v33, 0xa0, v160
	v_mad_i64_i32 v[34:35], s[24:25], v33, s57, v[162:163]
	v_lshl_add_u64 v[34:35], v[34:35], 0, v[166:167]
	v_fmamk_f32 v32, v246, 0x3a800000, v175
	v_rsq_f32_e32 v32, v32
	s_nop 0
	v_pk_fma_f32 v[28:29], v[28:29], v[32:33], v[112:113] op_sel_hi:[1,0,1]
	v_pk_fma_f32 v[30:31], v[30:31], v[32:33], v[114:115] op_sel_hi:[1,0,1]
	v_pk_fma_f32 v[24:25], v[24:25], v[32:33], v[104:105] op_sel_hi:[1,0,1]
	v_pk_fma_f32 v[26:27], v[26:27], v[32:33], v[106:107] op_sel_hi:[1,0,1]
	v_pk_fma_f32 v[20:21], v[20:21], v[32:33], v[116:117] op_sel_hi:[1,0,1]
	v_pk_fma_f32 v[22:23], v[22:23], v[32:33], v[118:119] op_sel_hi:[1,0,1]
	v_pk_fma_f32 v[16:17], v[16:17], v[32:33], v[108:109] op_sel_hi:[1,0,1]
	v_pk_fma_f32 v[18:19], v[18:19], v[32:33], v[110:111] op_sel_hi:[1,0,1]
	v_mul_f32_e32 v32, 0xbfb8aa3b, v28
	v_mul_f32_e32 v33, 0xbfb8aa3b, v29
	v_mul_f32_e32 v36, 0xbfb8aa3b, v30
	v_mul_f32_e32 v37, 0xbfb8aa3b, v31
	v_mul_f32_e32 v38, 0xbfb8aa3b, v24
	v_mul_f32_e32 v39, 0xbfb8aa3b, v25
	v_mul_f32_e32 v40, 0xbfb8aa3b, v26
	v_mul_f32_e32 v41, 0xbfb8aa3b, v27
	v_exp_f32_e32 v32, v32
	v_exp_f32_e32 v33, v33
	v_exp_f32_e32 v36, v36
	v_exp_f32_e32 v37, v37
	v_exp_f32_e32 v38, v38
	v_exp_f32_e32 v39, v39
	v_exp_f32_e32 v40, v40
	v_exp_f32_e32 v41, v41
	v_add_f32_e32 v32, 1.0, v32
	v_add_f32_e32 v33, 1.0, v33
	v_add_f32_e32 v36, 1.0, v36
	v_add_f32_e32 v37, 1.0, v37
	v_add_f32_e32 v38, 1.0, v38
	v_add_f32_e32 v39, 1.0, v39
	v_add_f32_e32 v40, 1.0, v40
	v_add_f32_e32 v41, 1.0, v41
	v_rcp_f32_e32 v32, v32
	v_rcp_f32_e32 v33, v33
	v_rcp_f32_e32 v36, v36
	v_rcp_f32_e32 v37, v37
	v_rcp_f32_e32 v38, v38
	v_rcp_f32_e32 v39, v39
	v_rcp_f32_e32 v40, v40
	v_rcp_f32_e32 v41, v41
	v_pk_mul_f32 v[28:29], v[28:29], v[32:33]
	v_pk_mul_f32 v[30:31], v[30:31], v[36:37]
	v_pk_mul_f32 v[24:25], v[24:25], v[38:39]
	v_pk_mul_f32 v[26:27], v[26:27], v[40:41]
	v_pk_mul_f32 v[20:21], v[20:21], v[28:29]
	v_pk_mul_f32 v[22:23], v[22:23], v[30:31]
	v_pk_mul_f32 v[24:25], v[16:17], v[24:25]
	v_pk_mul_f32 v[26:27], v[18:19], v[26:27]
	v_cvt_pk_f16_f32 v16, v20, v21
	v_cvt_pk_f16_f32 v17, v22, v23
	v_cvt_pk_f16_f32 v18, v24, v25
	v_cvt_pk_f16_f32 v19, v26, v27
	global_store_dwordx4 v[34:35], v[16:19], off
	s_nop 0
	s_nop 0
	v_add_u32_e32 v17, 0xb0, v160
	v_mad_i64_i32 v[18:19], s[24:25], v17, s57, v[162:163]
	v_lshl_add_u64 v[18:19], v[18:19], 0, v[166:167]
	v_fmamk_f32 v16, v247, 0x3a800000, v175
	v_rsq_f32_e32 v16, v16
	s_nop 0
	v_pk_fma_f32 v[12:13], v[12:13], v[16:17], v[112:113] op_sel_hi:[1,0,1]
	v_pk_fma_f32 v[14:15], v[14:15], v[16:17], v[114:115] op_sel_hi:[1,0,1]
	v_pk_fma_f32 v[8:9], v[8:9], v[16:17], v[104:105] op_sel_hi:[1,0,1]
	v_pk_fma_f32 v[10:11], v[10:11], v[16:17], v[106:107] op_sel_hi:[1,0,1]
	v_pk_fma_f32 v[4:5], v[4:5], v[16:17], v[116:117] op_sel_hi:[1,0,1]
	v_pk_fma_f32 v[6:7], v[6:7], v[16:17], v[118:119] op_sel_hi:[1,0,1]
	v_pk_fma_f32 v[0:1], v[0:1], v[16:17], v[108:109] op_sel_hi:[1,0,1]
	v_pk_fma_f32 v[2:3], v[2:3], v[16:17], v[110:111] op_sel_hi:[1,0,1]
	v_mul_f32_e32 v16, 0xbfb8aa3b, v12
	v_mul_f32_e32 v17, 0xbfb8aa3b, v13
	v_mul_f32_e32 v20, 0xbfb8aa3b, v14
	v_mul_f32_e32 v21, 0xbfb8aa3b, v15
	v_mul_f32_e32 v22, 0xbfb8aa3b, v8
	v_mul_f32_e32 v23, 0xbfb8aa3b, v9
	v_mul_f32_e32 v24, 0xbfb8aa3b, v10
	v_mul_f32_e32 v25, 0xbfb8aa3b, v11
	v_exp_f32_e32 v16, v16
	v_exp_f32_e32 v17, v17
	v_exp_f32_e32 v20, v20
	v_exp_f32_e32 v21, v21
	v_exp_f32_e32 v22, v22
	v_exp_f32_e32 v23, v23
	v_exp_f32_e32 v24, v24
	v_exp_f32_e32 v25, v25
	v_add_f32_e32 v16, 1.0, v16
	v_add_f32_e32 v17, 1.0, v17
	v_add_f32_e32 v20, 1.0, v20
	v_add_f32_e32 v21, 1.0, v21
	v_add_f32_e32 v22, 1.0, v22
	v_add_f32_e32 v23, 1.0, v23
	v_add_f32_e32 v24, 1.0, v24
	v_add_f32_e32 v25, 1.0, v25
	v_rcp_f32_e32 v16, v16
	v_rcp_f32_e32 v17, v17
	v_rcp_f32_e32 v20, v20
	v_rcp_f32_e32 v21, v21
	v_rcp_f32_e32 v22, v22
	v_rcp_f32_e32 v23, v23
	v_rcp_f32_e32 v24, v24
	v_rcp_f32_e32 v25, v25
	v_pk_mul_f32 v[12:13], v[12:13], v[16:17]
	v_pk_mul_f32 v[14:15], v[14:15], v[20:21]
	v_pk_mul_f32 v[8:9], v[8:9], v[22:23]
	v_pk_mul_f32 v[10:11], v[10:11], v[24:25]
	v_pk_mul_f32 v[4:5], v[4:5], v[12:13]
	v_pk_mul_f32 v[6:7], v[6:7], v[14:15]
	v_pk_mul_f32 v[8:9], v[0:1], v[8:9]
	v_pk_mul_f32 v[10:11], v[2:3], v[10:11]
	v_cvt_pk_f16_f32 v0, v4, v5
	v_cvt_pk_f16_f32 v1, v6, v7
	v_cvt_pk_f16_f32 v2, v8, v9
	v_cvt_pk_f16_f32 v3, v10, v11
	global_store_dwordx4 v[18:19], v[0:3], off
	s_cbranch_vccnz .LBB0_1581
	s_andn2_b64 vcc, exec, s[4:5]
	s_cbranch_vccnz .LBB0_1580
	s_barrier
	s_branch .LBB0_1580

	.amdhsa_kernel _Z14fwd_megakernel4Args
		.amdhsa_group_segment_fixed_size 0
		.amdhsa_private_segment_fixed_size 0
		.amdhsa_kernarg_size 472
		.amdhsa_user_sgpr_count 2
		.amdhsa_user_sgpr_dispatch_ptr 0
		.amdhsa_user_sgpr_queue_ptr 0
		.amdhsa_user_sgpr_kernarg_segment_ptr 1
		.amdhsa_user_sgpr_dispatch_id 0
		.amdhsa_user_sgpr_kernarg_preload_length 0
		.amdhsa_user_sgpr_kernarg_preload_offset 0
		.amdhsa_user_sgpr_private_segment_size 0
		.amdhsa_uses_dynamic_stack 0
		.amdhsa_enable_private_segment 0
		.amdhsa_system_sgpr_workgroup_id_x 1
		.amdhsa_system_sgpr_workgroup_id_y 0
		.amdhsa_system_sgpr_workgroup_id_z 0
		.amdhsa_system_sgpr_workgroup_info 0
		.amdhsa_system_vgpr_workitem_id 2
		.amdhsa_next_free_vgpr 248
		.amdhsa_next_free_sgpr 102
		.amdhsa_accum_offset 248
		.amdhsa_reserve_vcc 1
		.amdhsa_float_round_mode_32 0
		.amdhsa_float_round_mode_16_64 0
		.amdhsa_float_denorm_mode_32 3
		.amdhsa_float_denorm_mode_16_64 3
		.amdhsa_dx10_clamp 1
		.amdhsa_ieee_mode 1
		.amdhsa_fp16_overflow 0
		.amdhsa_tg_split 0
		.amdhsa_exception_fp_ieee_invalid_op 0
		.amdhsa_exception_fp_denorm_src 0
		.amdhsa_exception_fp_ieee_div_zero 0
		.amdhsa_exception_fp_ieee_overflow 0
		.amdhsa_exception_fp_ieee_underflow 0
		.amdhsa_exception_fp_ieee_inexact 0
		.amdhsa_exception_int_div_zero 0
	.end_amdhsa_kernel
